# GEMM K-loops (all five): LDS-DMA staging rebalanced to 4 global_load_lds per phase (SA00 stage moved to phase 3, SA10 to next phase 1), vmcnt(4) at phases 2 and 4
# speedup vs baseline: 1.0163x; 1.0110x over previous
; #define PG8_STAGE(bufoff, gbase, voff) do { _Pragma("unroll") for (int _i = 0; _i < 2; ++_i) \
;         __builtin_amdgcn_global_load_lds((const unsigned*)((const char*)(gbase) + (voff)[_i]), (LAS unsigned*)(lds + (bufoff) + ldsw + _i * 8192), 16, 0, 0); } while (0)
; #define PG8_LDA(dst, b, h) do { _Pragma("unroll") for (int m = 0; m < 4; ++m) _Pragma("unroll") for (int k = 0; k < 2; ++k) dst[m][k] = *(const LAS bf16x8*)(lds + PG8_SA(b, h) + aoff + m * 2048 + k * 1024); } while (0)
; #define PG8_LDB(dst, b, h) do { _Pragma("unroll") for (int n = 0; n < 2; ++n) _Pragma("unroll") for (int k = 0; k < 2; ++k) dst[n][k] = *(const LAS bf16x8*)(lds + PG8_SB(b, h) + boff + n * 2048 + k * 1024); } while (0)
; #define PG8_MMA(ai, bj, At, Bt) do { __builtin_amdgcn_s_setprio(1); _Pragma("unroll") for (int m = 0; m < 4; ++m) _Pragma("unroll") for (int n = 0; n < 2; ++n) _Pragma("unroll") for (int k = 0; k < 2; ++k) \
;         acc[ai][bj][m][n] = __builtin_amdgcn_mfma_f32_16x16x32_bf16(Bt[n][k], At[m][k], acc[ai][bj][m][n], 0, 0, 0); __builtin_amdgcn_s_setprio(0); } while (0)
; #define PG8_WAIT_V(n) asm volatile("s_waitcnt vmcnt(" #n ")" ::: "memory")
; #define PG8_BAR __builtin_amdgcn_s_barrier()
; template <class Epi, bool ALIGN_EPI>
; __device__ __forceinline__ void gemm_phase(LAS unsigned char* lds, const int tid, const Gemm g, const StaticOrder& S, const Epi& E) {
;     ...
;         for (int t = 0; t < nt; t += 2) {
;             if constexpr (Epi::HOOK) { if (t != 0 && (t & 7) == 0) E.hook(acc, cur, (t >> 3) - 1, wr, wc, fr, fq); }
;             const bool last = (t == nt - 2);
;             const char* a1 = cA + (size_t)(t + 1) * kstepA;
;             const char* a2 = last ? nA : cA + (size_t)(t + 2) * kstepA; const char* b2 = last ? nB : cB + (size_t)(t + 2) * kstepB;
;             const char* a3 = a2 + kstepA; const char* b3 = b2 + kstepB;
;             PG8_LDB(B0, 0, 0); PG8_LDB(B1, 0, 1); PG8_SCHED; PG8_LDA(At, 0, 0); PG8_STAGE(PG8_SA(1, 1), a1 + hstepA, voffA);
;             PG8_WAIT_V(8); PG8_WAIT_L(0); PG8_BAR; PG8_MMA(0, 0, At, B0); PG8_MMA(0, 1, At, B1); PG8_BAR; PG8_SCHED;
;             PG8_LDA(At, 0, 1); PG8_STAGE(PG8_SB(0, 0), b2, voffB); PG8_STAGE(PG8_SB(0, 1), b2 + hstepB, voffB); PG8_STAGE(PG8_SA(0, 0), a2, voffA);
;             PG8_WAIT_V(8); PG8_WAIT_L(0); PG8_BAR; PG8_MMA(1, 0, At, B0); PG8_MMA(1, 1, At, B1); PG8_BAR; PG8_SCHED;
.LBB0_113:
	s_add_i32 s90, s90, 2
	s_and_b64 s[34:35], exec, s[34:35]
	s_cselect_b32 s55, s23, s27
	s_cselect_b32 s54, s22, s25
	s_add_u32 s34, s92, 0x120000
	s_addc_u32 s35, s93, 0
	s_add_i32 s91, 0, 0x10000
	s_add_i32 s96, 0, 0x14000
	v_add_u32_e32 v148, s91, v175
	v_add_u32_e32 v164, s96, v175
	ds_read_b128 v[136:139], v148
	ds_read_b128 v[140:143], v148 offset:1024
	ds_read_b128 v[144:147], v148 offset:2048
	ds_read_b128 v[148:151], v148 offset:3072
	ds_read_b128 v[152:155], v164
	ds_read_b128 v[156:159], v164 offset:1024
	ds_read_b128 v[160:163], v164 offset:2048
	ds_read_b128 v[164:167], v164 offset:3072
	v_lshl_add_u64 v[172:173], s[30:31], 0, v[134:135]
	s_add_i32 m0, s56, 0xc000
	ds_read_b128 v[168:171], v177
	ds_read_b128 v[178:181], v177 offset:1024
	ds_read_b128 v[182:185], v177 offset:2048
	ds_read_b128 v[186:189], v177 offset:3072
	ds_read_b128 v[190:193], v177 offset:4096
	ds_read_b128 v[210:213], v177 offset:5120
	ds_read_b128 v[214:217], v177 offset:6144
	ds_read_b128 v[218:221], v177 offset:7168
	global_load_lds_dwordx4 v[172:173], off
	v_lshl_add_u64 v[172:173], s[30:31], 0, v[132:133]
	s_add_i32 m0, s56, 0xe000
	s_nop 0
	global_load_lds_dwordx4 v[172:173], off
	s_sub_u32 s98, s30, 0x4000
	s_subb_u32 s99, s31, 0
	v_lshl_add_u64 v[172:173], s[98:99], 0, v[134:135]
	s_mov_b32 m0, s70
	s_nop 0
	global_load_lds_dwordx4 v[172:173], off
	v_lshl_add_u64 v[172:173], s[98:99], 0, v[132:133]
	s_mov_b32 m0, s71
	s_nop 0
	global_load_lds_dwordx4 v[172:173], off
	s_waitcnt vmcnt(8)
	s_waitcnt lgkmcnt(0)
	s_barrier
	s_setprio 1
	s_waitcnt lgkmcnt(0)
	v_mfma_f32_16x16x32_bf16 v[126:129], v[136:139], v[168:171], v[126:129]
	v_mfma_f32_16x16x32_bf16 v[94:97], v[144:147], v[168:171], v[94:97]
	v_mfma_f32_16x16x32_bf16 v[122:125], v[136:139], v[182:185], v[122:125]
	v_mfma_f32_16x16x32_bf16 v[90:93], v[144:147], v[182:185], v[90:93]
	v_mfma_f32_16x16x32_bf16 v[118:121], v[136:139], v[190:193], v[118:121]
	v_mfma_f32_16x16x32_bf16 v[86:89], v[144:147], v[190:193], v[86:89]
	v_mfma_f32_16x16x32_bf16 v[114:117], v[136:139], v[214:217], v[114:117]
	v_mfma_f32_16x16x32_bf16 v[82:85], v[144:147], v[214:217], v[82:85]
	v_mfma_f32_16x16x32_bf16 v[126:129], v[140:143], v[178:181], v[126:129]
	v_mfma_f32_16x16x32_bf16 v[94:97], v[148:151], v[178:181], v[94:97]
	v_mfma_f32_16x16x32_bf16 v[122:125], v[140:143], v[186:189], v[122:125]
	v_mfma_f32_16x16x32_bf16 v[90:93], v[148:151], v[186:189], v[90:93]
	v_mfma_f32_16x16x32_bf16 v[118:121], v[140:143], v[210:213], v[118:121]
	v_mfma_f32_16x16x32_bf16 v[86:89], v[148:151], v[210:213], v[86:89]
	v_mfma_f32_16x16x32_bf16 v[114:117], v[140:143], v[218:221], v[114:117]
	v_mfma_f32_16x16x32_bf16 v[82:85], v[148:151], v[218:221], v[82:85]
	s_setprio 0
	s_setprio 1
	v_mfma_f32_16x16x32_bf16 v[62:65], v[152:155], v[168:171], v[62:65]
	v_mfma_f32_16x16x32_bf16 v[38:41], v[160:163], v[168:171], v[38:41]
	v_mfma_f32_16x16x32_bf16 v[58:61], v[152:155], v[182:185], v[58:61]
	v_mfma_f32_16x16x32_bf16 v[30:33], v[160:163], v[182:185], v[30:33]
	v_mfma_f32_16x16x32_bf16 v[54:57], v[152:155], v[190:193], v[54:57]
	v_mfma_f32_16x16x32_bf16 v[22:25], v[160:163], v[190:193], v[22:25]
	v_mfma_f32_16x16x32_bf16 v[50:53], v[152:155], v[214:217], v[50:53]
	v_mfma_f32_16x16x32_bf16 v[18:21], v[160:163], v[214:217], v[18:21]
	v_mfma_f32_16x16x32_bf16 v[62:65], v[156:159], v[178:181], v[62:65]
	v_mfma_f32_16x16x32_bf16 v[38:41], v[164:167], v[178:181], v[38:41]
	v_mfma_f32_16x16x32_bf16 v[58:61], v[156:159], v[186:189], v[58:61]
	v_mfma_f32_16x16x32_bf16 v[30:33], v[164:167], v[186:189], v[30:33]
	v_mfma_f32_16x16x32_bf16 v[54:57], v[156:159], v[210:213], v[54:57]
	v_mfma_f32_16x16x32_bf16 v[22:25], v[164:167], v[210:213], v[22:25]
	v_mfma_f32_16x16x32_bf16 v[50:53], v[156:159], v[218:221], v[50:53]
	v_mfma_f32_16x16x32_bf16 v[18:21], v[164:167], v[218:221], v[18:21]
	s_setprio 0
	s_barrier
	s_add_i32 s91, s91, s29
	v_lshl_add_u64 v[172:173], s[54:55], 0, v[0:1]
	s_mov_b32 m0, s91
	ds_read_b128 v[168:171], v177 offset:16384
	ds_read_b128 v[178:181], v177 offset:17408
	ds_read_b128 v[182:185], v177 offset:18432
	ds_read_b128 v[186:189], v177 offset:19456
	ds_read_b128 v[190:193], v177 offset:20480
	ds_read_b128 v[210:213], v177 offset:21504
	ds_read_b128 v[214:217], v177 offset:22528
	ds_read_b128 v[218:221], v177 offset:23552
	global_load_lds_dwordx4 v[172:173], off
	s_add_i32 m0, s91, 0x2000
	s_add_u32 s94, s54, 0x4000
	v_lshl_add_u64 v[172:173], s[54:55], 0, v[130:131]
	s_addc_u32 s95, s55, 0
	s_add_i32 s91, s96, s29
	global_load_lds_dwordx4 v[172:173], off
	v_lshl_add_u64 v[172:173], s[94:95], 0, v[0:1]
	s_mov_b32 m0, s91
	s_nop 0
	global_load_lds_dwordx4 v[172:173], off
	v_lshl_add_u64 v[172:173], s[94:95], 0, v[130:131]
	s_add_i32 m0, s91, 0x2000
	s_nop 0
	global_load_lds_dwordx4 v[172:173], off
	s_waitcnt vmcnt(4)
	s_waitcnt lgkmcnt(0)
	s_barrier
; #define PG8_STAGE(bufoff, gbase, voff) do { _Pragma("unroll") for (int _i = 0; _i < 2; ++_i) \
;         __builtin_amdgcn_global_load_lds((const unsigned*)((const char*)(gbase) + (voff)[_i]), (LAS unsigned*)(lds + (bufoff) + ldsw + _i * 8192), 16, 0, 0); } while (0)
; #define PG8_LDA(dst, b, h) do { _Pragma("unroll") for (int m = 0; m < 4; ++m) _Pragma("unroll") for (int k = 0; k < 2; ++k) dst[m][k] = *(const LAS bf16x8*)(lds + PG8_SA(b, h) + aoff + m * 2048 + k * 1024); } while (0)
; #define PG8_LDB(dst, b, h) do { _Pragma("unroll") for (int n = 0; n < 2; ++n) _Pragma("unroll") for (int k = 0; k < 2; ++k) dst[n][k] = *(const LAS bf16x8*)(lds + PG8_SB(b, h) + boff + n * 2048 + k * 1024); } while (0)
; #define PG8_MMA(ai, bj, At, Bt) do { __builtin_amdgcn_s_setprio(1); _Pragma("unroll") for (int m = 0; m < 4; ++m) _Pragma("unroll") for (int n = 0; n < 2; ++n) _Pragma("unroll") for (int k = 0; k < 2; ++k) \
;         acc[ai][bj][m][n] = __builtin_amdgcn_mfma_f32_16x16x32_bf16(Bt[n][k], At[m][k], acc[ai][bj][m][n], 0, 0, 0); __builtin_amdgcn_s_setprio(0); } while (0)
; #define PG8_WAIT_V(n) asm volatile("s_waitcnt vmcnt(" #n ")" ::: "memory")
; #define PG8_WAIT_L(n) asm volatile("s_waitcnt lgkmcnt(" #n ")" ::: "memory")
; #define PG8_BAR __builtin_amdgcn_s_barrier()
; #define PG8_SCHED __builtin_amdgcn_sched_barrier(0)
; template <class Epi, bool ALIGN_EPI>
; __device__ __forceinline__ void gemm_phase(LAS unsigned char* lds, const int tid, const Gemm g, const StaticOrder& S, const Epi& E) {
;     ...
;             PG8_WAIT_V(8); PG8_WAIT_L(0); PG8_BAR; PG8_MMA(1, 0, At, B0); PG8_MMA(1, 1, At, B1); PG8_BAR; PG8_SCHED;
;             PG8_LDB(B0, 1, 0); PG8_LDB(B1, 1, 1); PG8_SCHED; PG8_LDA(At, 1, 0); PG8_STAGE(PG8_SA(0, 1), a2 + hstepA, voffA);
;             PG8_WAIT_V(8); PG8_WAIT_L(0); PG8_BAR; PG8_MMA(0, 0, At, B0); PG8_MMA(0, 1, At, B1); PG8_BAR; PG8_SCHED;
	s_setprio 1
	s_waitcnt lgkmcnt(0)
	v_mfma_f32_16x16x32_bf16 v[110:113], v[136:139], v[168:171], v[110:113]
	v_mfma_f32_16x16x32_bf16 v[78:81], v[144:147], v[168:171], v[78:81]
	v_mfma_f32_16x16x32_bf16 v[106:109], v[136:139], v[182:185], v[106:109]
	v_mfma_f32_16x16x32_bf16 v[74:77], v[144:147], v[182:185], v[74:77]
	v_mfma_f32_16x16x32_bf16 v[102:105], v[136:139], v[190:193], v[102:105]
	v_mfma_f32_16x16x32_bf16 v[70:73], v[144:147], v[190:193], v[70:73]
	v_mfma_f32_16x16x32_bf16 v[98:101], v[136:139], v[214:217], v[98:101]
	v_mfma_f32_16x16x32_bf16 v[66:69], v[144:147], v[214:217], v[66:69]
	v_mfma_f32_16x16x32_bf16 v[110:113], v[140:143], v[178:181], v[110:113]
	v_mfma_f32_16x16x32_bf16 v[78:81], v[148:151], v[178:181], v[78:81]
	v_mfma_f32_16x16x32_bf16 v[106:109], v[140:143], v[186:189], v[106:109]
	v_mfma_f32_16x16x32_bf16 v[74:77], v[148:151], v[186:189], v[74:77]
	v_mfma_f32_16x16x32_bf16 v[102:105], v[140:143], v[210:213], v[102:105]
	v_mfma_f32_16x16x32_bf16 v[70:73], v[148:151], v[210:213], v[70:73]
	v_mfma_f32_16x16x32_bf16 v[98:101], v[140:143], v[218:221], v[98:101]
	v_mfma_f32_16x16x32_bf16 v[66:69], v[148:151], v[218:221], v[66:69]
	s_setprio 0
	s_setprio 1
	v_mfma_f32_16x16x32_bf16 v[46:49], v[152:155], v[168:171], v[46:49]
	v_mfma_f32_16x16x32_bf16 v[14:17], v[160:163], v[168:171], v[14:17]
	v_mfma_f32_16x16x32_bf16 v[42:45], v[152:155], v[182:185], v[42:45]
	v_mfma_f32_16x16x32_bf16 v[10:13], v[160:163], v[182:185], v[10:13]
	v_mfma_f32_16x16x32_bf16 v[34:37], v[152:155], v[190:193], v[34:37]
	v_mfma_f32_16x16x32_bf16 v[6:9], v[160:163], v[190:193], v[6:9]
	v_mfma_f32_16x16x32_bf16 v[26:29], v[152:155], v[214:217], v[26:29]
	v_mfma_f32_16x16x32_bf16 v[2:5], v[160:163], v[214:217], v[2:5]
	v_mfma_f32_16x16x32_bf16 v[46:49], v[156:159], v[178:181], v[46:49]
	v_mfma_f32_16x16x32_bf16 v[14:17], v[164:167], v[178:181], v[14:17]
	v_mfma_f32_16x16x32_bf16 v[42:45], v[156:159], v[186:189], v[42:45]
	v_mfma_f32_16x16x32_bf16 v[10:13], v[164:167], v[186:189], v[10:13]
	v_mfma_f32_16x16x32_bf16 v[34:37], v[156:159], v[210:213], v[34:37]
	v_mfma_f32_16x16x32_bf16 v[6:9], v[164:167], v[210:213], v[6:9]
	v_mfma_f32_16x16x32_bf16 v[26:29], v[156:159], v[218:221], v[26:29]
	v_mfma_f32_16x16x32_bf16 v[2:5], v[164:167], v[218:221], v[2:5]
	s_setprio 0
	s_barrier
	s_add_i32 s91, 0, 0x18000
	s_add_i32 s94, 0, 0x1c000
	v_add_u32_e32 v148, s91, v175
	v_add_u32_e32 v164, s94, v175
	ds_read_b128 v[136:139], v148
	ds_read_b128 v[140:143], v148 offset:1024
	ds_read_b128 v[144:147], v148 offset:2048
	ds_read_b128 v[148:151], v148 offset:3072
	ds_read_b128 v[152:155], v164
	ds_read_b128 v[156:159], v164 offset:1024
	ds_read_b128 v[160:163], v164 offset:2048
	ds_read_b128 v[164:167], v164 offset:3072
	v_lshl_add_u64 v[172:173], s[92:93], 0, v[0:1]
	s_mov_b32 m0, s56
	s_nop 0
	global_load_lds_dwordx4 v[172:173], off
	v_lshl_add_u64 v[172:173], s[92:93], 0, v[130:131]
	s_mov_b32 m0, s58
	s_nop 0
	global_load_lds_dwordx4 v[172:173], off
	s_add_u32 s92, s92, 0x4000
	s_addc_u32 s93, s93, 0
	s_mov_b32 m0, s63
	v_lshl_add_u64 v[172:173], s[92:93], 0, v[0:1]
	ds_read_b128 v[168:171], v177 offset:32768
	ds_read_b128 v[178:181], v177 offset:33792
	ds_read_b128 v[182:185], v177 offset:34816
	ds_read_b128 v[186:189], v177 offset:35840
	ds_read_b128 v[190:193], v177 offset:36864
	ds_read_b128 v[210:213], v177 offset:37888
	ds_read_b128 v[214:217], v177 offset:38912
	ds_read_b128 v[218:221], v177 offset:39936
	global_load_lds_dwordx4 v[172:173], off
	v_lshl_add_u64 v[172:173], s[92:93], 0, v[130:131]
	s_mov_b32 m0, s64
	s_nop 0
	global_load_lds_dwordx4 v[172:173], off
	s_waitcnt vmcnt(8)
	s_waitcnt lgkmcnt(0)
	s_barrier
; #define PG8_STAGE(bufoff, gbase, voff) do { _Pragma("unroll") for (int _i = 0; _i < 2; ++_i) \
;         __builtin_amdgcn_global_load_lds((const unsigned*)((const char*)(gbase) + (voff)[_i]), (LAS unsigned*)(lds + (bufoff) + ldsw + _i * 8192), 16, 0, 0); } while (0)
; #define PG8_LDA(dst, b, h) do { _Pragma("unroll") for (int m = 0; m < 4; ++m) _Pragma("unroll") for (int k = 0; k < 2; ++k) dst[m][k] = *(const LAS bf16x8*)(lds + PG8_SA(b, h) + aoff + m * 2048 + k * 1024); } while (0)
; #define PG8_MMA(ai, bj, At, Bt) do { __builtin_amdgcn_s_setprio(1); _Pragma("unroll") for (int m = 0; m < 4; ++m) _Pragma("unroll") for (int n = 0; n < 2; ++n) _Pragma("unroll") for (int k = 0; k < 2; ++k) \
;         acc[ai][bj][m][n] = __builtin_amdgcn_mfma_f32_16x16x32_bf16(Bt[n][k], At[m][k], acc[ai][bj][m][n], 0, 0, 0); __builtin_amdgcn_s_setprio(0); } while (0)
; #define PG8_WAIT_V(n) asm volatile("s_waitcnt vmcnt(" #n ")" ::: "memory")
; #define PG8_WAIT_L(n) asm volatile("s_waitcnt lgkmcnt(" #n ")" ::: "memory")
; #define PG8_BAR __builtin_amdgcn_s_barrier()
; #define PG8_SCHED __builtin_amdgcn_sched_barrier(0)
; template <class Epi, bool ALIGN_EPI>
; __device__ __forceinline__ void gemm_phase(LAS unsigned char* lds, const int tid, const Gemm g, const StaticOrder& S, const Epi& E) {
;     ...
;             PG8_WAIT_V(8); PG8_WAIT_L(0); PG8_BAR; PG8_MMA(0, 0, At, B0); PG8_MMA(0, 1, At, B1); PG8_BAR; PG8_SCHED;
;             PG8_LDA(At, 1, 1); PG8_STAGE(PG8_SB(1, 0), b3, voffB); PG8_STAGE(PG8_SB(1, 1), b3 + hstepB, voffB); PG8_STAGE(PG8_SA(1, 0), a3, voffA);
;             PG8_WAIT_V(8); PG8_WAIT_L(0); PG8_BAR; PG8_MMA(1, 0, At, B0); PG8_MMA(1, 1, At, B1); PG8_BAR; PG8_SCHED;
;         }
	s_setprio 1
	s_waitcnt lgkmcnt(0)
	v_mfma_f32_16x16x32_bf16 v[126:129], v[136:139], v[168:171], v[126:129]
	v_mfma_f32_16x16x32_bf16 v[94:97], v[144:147], v[168:171], v[94:97]
	v_mfma_f32_16x16x32_bf16 v[122:125], v[136:139], v[182:185], v[122:125]
	v_mfma_f32_16x16x32_bf16 v[90:93], v[144:147], v[182:185], v[90:93]
	v_mfma_f32_16x16x32_bf16 v[118:121], v[136:139], v[190:193], v[118:121]
	v_mfma_f32_16x16x32_bf16 v[86:89], v[144:147], v[190:193], v[86:89]
	v_mfma_f32_16x16x32_bf16 v[114:117], v[136:139], v[214:217], v[114:117]
	v_mfma_f32_16x16x32_bf16 v[82:85], v[144:147], v[214:217], v[82:85]
	v_mfma_f32_16x16x32_bf16 v[126:129], v[140:143], v[178:181], v[126:129]
	v_mfma_f32_16x16x32_bf16 v[94:97], v[148:151], v[178:181], v[94:97]
	v_mfma_f32_16x16x32_bf16 v[122:125], v[140:143], v[186:189], v[122:125]
	v_mfma_f32_16x16x32_bf16 v[90:93], v[148:151], v[186:189], v[90:93]
	v_mfma_f32_16x16x32_bf16 v[118:121], v[140:143], v[210:213], v[118:121]
	v_mfma_f32_16x16x32_bf16 v[86:89], v[148:151], v[210:213], v[86:89]
	v_mfma_f32_16x16x32_bf16 v[114:117], v[140:143], v[218:221], v[114:117]
	v_mfma_f32_16x16x32_bf16 v[82:85], v[148:151], v[218:221], v[82:85]
	s_setprio 0
	s_setprio 1
	v_mfma_f32_16x16x32_bf16 v[62:65], v[152:155], v[168:171], v[62:65]
	v_mfma_f32_16x16x32_bf16 v[38:41], v[160:163], v[168:171], v[38:41]
	v_mfma_f32_16x16x32_bf16 v[58:61], v[152:155], v[182:185], v[58:61]
	v_mfma_f32_16x16x32_bf16 v[30:33], v[160:163], v[182:185], v[30:33]
	v_mfma_f32_16x16x32_bf16 v[54:57], v[152:155], v[190:193], v[54:57]
	v_mfma_f32_16x16x32_bf16 v[22:25], v[160:163], v[190:193], v[22:25]
	v_mfma_f32_16x16x32_bf16 v[50:53], v[152:155], v[214:217], v[50:53]
	v_mfma_f32_16x16x32_bf16 v[18:21], v[160:163], v[214:217], v[18:21]
	v_mfma_f32_16x16x32_bf16 v[62:65], v[156:159], v[178:181], v[62:65]
	v_mfma_f32_16x16x32_bf16 v[38:41], v[164:167], v[178:181], v[38:41]
	v_mfma_f32_16x16x32_bf16 v[58:61], v[156:159], v[186:189], v[58:61]
	v_mfma_f32_16x16x32_bf16 v[30:33], v[164:167], v[186:189], v[30:33]
	v_mfma_f32_16x16x32_bf16 v[54:57], v[156:159], v[210:213], v[54:57]
	v_mfma_f32_16x16x32_bf16 v[22:25], v[164:167], v[210:213], v[22:25]
	v_mfma_f32_16x16x32_bf16 v[50:53], v[156:159], v[218:221], v[50:53]
	v_mfma_f32_16x16x32_bf16 v[18:21], v[164:167], v[218:221], v[18:21]
	s_setprio 0
	s_barrier
	s_add_u32 s92, s54, 0x40000
	s_addc_u32 s93, s55, 0
	s_add_i32 s91, s91, s29
	v_lshl_add_u64 v[172:173], s[92:93], 0, v[0:1]
	s_mov_b32 m0, s91
	ds_read_b128 v[168:171], v177 offset:49152
	ds_read_b128 v[178:181], v177 offset:50176
	ds_read_b128 v[182:185], v177 offset:51200
	ds_read_b128 v[186:189], v177 offset:52224
	ds_read_b128 v[190:193], v177 offset:53248
	ds_read_b128 v[210:213], v177 offset:54272
	ds_read_b128 v[214:217], v177 offset:55296
	ds_read_b128 v[218:221], v177 offset:56320
	global_load_lds_dwordx4 v[172:173], off
	s_add_i32 m0, s91, 0x2000
	s_add_u32 s54, s54, 0x44000
	v_lshl_add_u64 v[172:173], s[92:93], 0, v[130:131]
	s_addc_u32 s55, s55, 0
	s_add_i32 s91, s94, s29
	global_load_lds_dwordx4 v[172:173], off
	v_lshl_add_u64 v[172:173], s[54:55], 0, v[0:1]
	s_mov_b32 m0, s91
	s_nop 0
	global_load_lds_dwordx4 v[172:173], off
	v_lshl_add_u64 v[172:173], s[54:55], 0, v[130:131]
	s_add_i32 m0, s91, 0x2000
	s_nop 0
	global_load_lds_dwordx4 v[172:173], off
	s_waitcnt vmcnt(4)
	s_waitcnt lgkmcnt(0)
	s_barrier
	s_setprio 1
	s_waitcnt lgkmcnt(0)
	v_mfma_f32_16x16x32_bf16 v[110:113], v[136:139], v[168:171], v[110:113]
	v_mfma_f32_16x16x32_bf16 v[78:81], v[144:147], v[168:171], v[78:81]
	v_mfma_f32_16x16x32_bf16 v[106:109], v[136:139], v[182:185], v[106:109]
	v_mfma_f32_16x16x32_bf16 v[74:77], v[144:147], v[182:185], v[74:77]
	v_mfma_f32_16x16x32_bf16 v[102:105], v[136:139], v[190:193], v[102:105]
	v_mfma_f32_16x16x32_bf16 v[70:73], v[144:147], v[190:193], v[70:73]
	v_mfma_f32_16x16x32_bf16 v[98:101], v[136:139], v[214:217], v[98:101]
	v_mfma_f32_16x16x32_bf16 v[66:69], v[144:147], v[214:217], v[66:69]
	v_mfma_f32_16x16x32_bf16 v[110:113], v[140:143], v[178:181], v[110:113]
	v_mfma_f32_16x16x32_bf16 v[78:81], v[148:151], v[178:181], v[78:81]
	v_mfma_f32_16x16x32_bf16 v[106:109], v[140:143], v[186:189], v[106:109]
	v_mfma_f32_16x16x32_bf16 v[74:77], v[148:151], v[186:189], v[74:77]
	v_mfma_f32_16x16x32_bf16 v[102:105], v[140:143], v[210:213], v[102:105]
	v_mfma_f32_16x16x32_bf16 v[70:73], v[148:151], v[210:213], v[70:73]
	v_mfma_f32_16x16x32_bf16 v[98:101], v[140:143], v[218:221], v[98:101]
	v_mfma_f32_16x16x32_bf16 v[66:69], v[148:151], v[218:221], v[66:69]
	s_setprio 0
	s_setprio 1
	v_mfma_f32_16x16x32_bf16 v[46:49], v[152:155], v[168:171], v[46:49]
	v_mfma_f32_16x16x32_bf16 v[14:17], v[160:163], v[168:171], v[14:17]
	v_mfma_f32_16x16x32_bf16 v[42:45], v[152:155], v[182:185], v[42:45]
	v_mfma_f32_16x16x32_bf16 v[10:13], v[160:163], v[182:185], v[10:13]
	v_mfma_f32_16x16x32_bf16 v[34:37], v[152:155], v[190:193], v[34:37]
	v_mfma_f32_16x16x32_bf16 v[6:9], v[160:163], v[190:193], v[6:9]
	v_mfma_f32_16x16x32_bf16 v[26:29], v[152:155], v[214:217], v[26:29]
	v_mfma_f32_16x16x32_bf16 v[2:5], v[160:163], v[214:217], v[2:5]
	v_mfma_f32_16x16x32_bf16 v[46:49], v[156:159], v[178:181], v[46:49]
	v_mfma_f32_16x16x32_bf16 v[14:17], v[164:167], v[178:181], v[14:17]
	v_mfma_f32_16x16x32_bf16 v[42:45], v[156:159], v[186:189], v[42:45]
	v_mfma_f32_16x16x32_bf16 v[10:13], v[164:167], v[186:189], v[10:13]
	v_mfma_f32_16x16x32_bf16 v[34:37], v[156:159], v[210:213], v[34:37]
	v_mfma_f32_16x16x32_bf16 v[6:9], v[164:167], v[210:213], v[6:9]
	v_mfma_f32_16x16x32_bf16 v[26:29], v[156:159], v[218:221], v[26:29]
	v_mfma_f32_16x16x32_bf16 v[2:5], v[164:167], v[218:221], v[2:5]
	s_setprio 0
	s_barrier
	s_add_u32 s25, s25, 0x80000
	s_addc_u32 s27, s27, 0
	s_add_u32 s30, s30, 0x240000
	s_addc_u32 s31, s31, 0
	s_cmp_ge_u32 s90, s17
	s_cbranch_scc1 .LBB0_116

; #define PG8_STAGE(bufoff, gbase, voff) do { _Pragma("unroll") for (int _i = 0; _i < 2; ++_i) \
;         __builtin_amdgcn_global_load_lds((const unsigned*)((const char*)(gbase) + (voff)[_i]), (LAS unsigned*)(lds + (bufoff) + ldsw + _i * 8192), 16, 0, 0); } while (0)
; #define PG8_LDA(dst, b, h) do { _Pragma("unroll") for (int m = 0; m < 4; ++m) _Pragma("unroll") for (int k = 0; k < 2; ++k) dst[m][k] = *(const LAS bf16x8*)(lds + PG8_SA(b, h) + aoff + m * 2048 + k * 1024); } while (0)
; #define PG8_LDB(dst, b, h) do { _Pragma("unroll") for (int n = 0; n < 2; ++n) _Pragma("unroll") for (int k = 0; k < 2; ++k) dst[n][k] = *(const LAS bf16x8*)(lds + PG8_SB(b, h) + boff + n * 2048 + k * 1024); } while (0)
; #define PG8_MMA(ai, bj, At, Bt) do { __builtin_amdgcn_s_setprio(1); _Pragma("unroll") for (int m = 0; m < 4; ++m) _Pragma("unroll") for (int n = 0; n < 2; ++n) _Pragma("unroll") for (int k = 0; k < 2; ++k) \
;         acc[ai][bj][m][n] = __builtin_amdgcn_mfma_f32_16x16x32_bf16(Bt[n][k], At[m][k], acc[ai][bj][m][n], 0, 0, 0); __builtin_amdgcn_s_setprio(0); } while (0)
; #define PG8_WAIT_V(n) asm volatile("s_waitcnt vmcnt(" #n ")" ::: "memory")
; #define PG8_BAR __builtin_amdgcn_s_barrier()
; template <class Epi, bool ALIGN_EPI>
; __device__ __forceinline__ void gemm_phase(LAS unsigned char* lds, const int tid, const Gemm g, const StaticOrder& S, const Epi& E) {
;     ...
;         for (int t = 0; t < nt; t += 2) {
;             if constexpr (Epi::HOOK) { if (t != 0 && (t & 7) == 0) E.hook(acc, cur, (t >> 3) - 1, wr, wc, fr, fq); }
;             const bool last = (t == nt - 2);
;             const char* a1 = cA + (size_t)(t + 1) * kstepA;
;             const char* a2 = last ? nA : cA + (size_t)(t + 2) * kstepA; const char* b2 = last ? nB : cB + (size_t)(t + 2) * kstepB;
;             const char* a3 = a2 + kstepA; const char* b3 = b2 + kstepB;
;             PG8_LDB(B0, 0, 0); PG8_LDB(B1, 0, 1); PG8_SCHED; PG8_LDA(At, 0, 0); PG8_STAGE(PG8_SA(1, 1), a1 + hstepA, voffA);
;             PG8_WAIT_V(8); PG8_WAIT_L(0); PG8_BAR; PG8_MMA(0, 0, At, B0); PG8_MMA(0, 1, At, B1); PG8_BAR; PG8_SCHED;
;             PG8_LDA(At, 0, 1); PG8_STAGE(PG8_SB(0, 0), b2, voffB); PG8_STAGE(PG8_SB(0, 1), b2 + hstepB, voffB); PG8_STAGE(PG8_SA(0, 0), a2, voffA);
;             PG8_WAIT_V(8); PG8_WAIT_L(0); PG8_BAR; PG8_MMA(1, 0, At, B0); PG8_MMA(1, 1, At, B1); PG8_BAR; PG8_SCHED;
.LBB0_143:
	s_add_u32 s26, s24, 0xfff80080
	s_addc_u32 s27, s25, -1
	s_add_i32 s68, 0, 0x10000
	s_cmp_eq_u32 s67, 28
	s_cselect_b32 s29, s19, s27
	s_cselect_b32 s28, s18, s26
	v_add_u32_e32 v142, s68, v145
	s_cselect_b32 s27, s21, s17
	s_cselect_b32 s26, s20, s15
	s_add_i32 s70, 0, 0x14000
	ds_read_b128 v[148:151], v142
	ds_read_b128 v[152:155], v142 offset:1024
	ds_read_b128 v[156:159], v142 offset:2048
	ds_read_b128 v[160:163], v142 offset:3072
	v_add_u32_e32 v142, s70, v145
	ds_read_b128 v[164:167], v142
	ds_read_b128 v[168:171], v142 offset:1024
	ds_read_b128 v[172:175], v142 offset:2048
	ds_read_b128 v[176:179], v142 offset:3072
	v_lshl_add_u64 v[142:143], s[24:25], 0, v[140:141]
	s_add_i32 m0, s23, 0xc000
	ds_read_b128 v[180:183], v146
	ds_read_b128 v[184:187], v146 offset:1024
	ds_read_b128 v[188:191], v146 offset:2048
	ds_read_b128 v[192:195], v146 offset:3072
	ds_read_b128 v[210:213], v146 offset:4096
	ds_read_b128 v[214:217], v146 offset:5120
	ds_read_b128 v[218:221], v146 offset:6144
	ds_read_b128 v[222:225], v146 offset:7168
	global_load_lds_dwordx4 v[142:143], off
	v_lshl_add_u64 v[142:143], s[24:25], 0, v[138:139]
	s_add_i32 m0, s23, 0xe000
	s_nop 0
	global_load_lds_dwordx4 v[142:143], off
	s_sub_u32 s98, s24, 0x80000
	s_subb_u32 s99, s25, 0
	v_lshl_add_u64 v[142:143], s[98:99], 0, v[140:141]
	s_mov_b32 m0, s56
	s_nop 0
	global_load_lds_dwordx4 v[142:143], off
	v_lshl_add_u64 v[142:143], s[98:99], 0, v[138:139]
	s_mov_b32 m0, s58
	s_nop 0
	global_load_lds_dwordx4 v[142:143], off
	s_waitcnt vmcnt(8)
	s_waitcnt lgkmcnt(0)
	s_barrier
	s_setprio 1
	s_waitcnt lgkmcnt(0)
	v_mfma_f32_16x16x32_bf16 v[126:129], v[148:151], v[180:183], v[126:129]
	v_mfma_f32_16x16x32_bf16 v[122:125], v[156:159], v[180:183], v[122:125]
	v_mfma_f32_16x16x32_bf16 v[110:113], v[148:151], v[188:191], v[110:113]
	v_mfma_f32_16x16x32_bf16 v[106:109], v[156:159], v[188:191], v[106:109]
	v_mfma_f32_16x16x32_bf16 v[94:97], v[148:151], v[210:213], v[94:97]
	v_mfma_f32_16x16x32_bf16 v[90:93], v[156:159], v[210:213], v[90:93]
	v_mfma_f32_16x16x32_bf16 v[78:81], v[148:151], v[218:221], v[78:81]
	v_mfma_f32_16x16x32_bf16 v[74:77], v[156:159], v[218:221], v[74:77]
	v_mfma_f32_16x16x32_bf16 v[126:129], v[152:155], v[184:187], v[126:129]
	v_mfma_f32_16x16x32_bf16 v[122:125], v[160:163], v[184:187], v[122:125]
	v_mfma_f32_16x16x32_bf16 v[110:113], v[152:155], v[192:195], v[110:113]
	v_mfma_f32_16x16x32_bf16 v[106:109], v[160:163], v[192:195], v[106:109]
	v_mfma_f32_16x16x32_bf16 v[94:97], v[152:155], v[214:217], v[94:97]
	v_mfma_f32_16x16x32_bf16 v[90:93], v[160:163], v[214:217], v[90:93]
	v_mfma_f32_16x16x32_bf16 v[78:81], v[152:155], v[222:225], v[78:81]
	v_mfma_f32_16x16x32_bf16 v[74:77], v[160:163], v[222:225], v[74:77]
	s_setprio 0
	s_setprio 1
	v_mfma_f32_16x16x32_bf16 v[118:121], v[164:167], v[180:183], v[118:121]
	v_mfma_f32_16x16x32_bf16 v[114:117], v[172:175], v[180:183], v[114:117]
	v_mfma_f32_16x16x32_bf16 v[102:105], v[164:167], v[188:191], v[102:105]
	v_mfma_f32_16x16x32_bf16 v[98:101], v[172:175], v[188:191], v[98:101]
	v_mfma_f32_16x16x32_bf16 v[86:89], v[164:167], v[210:213], v[86:89]
	v_mfma_f32_16x16x32_bf16 v[82:85], v[172:175], v[210:213], v[82:85]
	v_mfma_f32_16x16x32_bf16 v[70:73], v[164:167], v[218:221], v[70:73]
	v_mfma_f32_16x16x32_bf16 v[66:69], v[172:175], v[218:221], v[66:69]
	v_mfma_f32_16x16x32_bf16 v[118:121], v[168:171], v[184:187], v[118:121]
	v_mfma_f32_16x16x32_bf16 v[114:117], v[176:179], v[184:187], v[114:117]
	v_mfma_f32_16x16x32_bf16 v[102:105], v[168:171], v[192:195], v[102:105]
	v_mfma_f32_16x16x32_bf16 v[98:101], v[176:179], v[192:195], v[98:101]
	v_mfma_f32_16x16x32_bf16 v[86:89], v[168:171], v[214:217], v[86:89]
	v_mfma_f32_16x16x32_bf16 v[82:85], v[176:179], v[214:217], v[82:85]
	v_mfma_f32_16x16x32_bf16 v[70:73], v[168:171], v[222:225], v[70:73]
	v_mfma_f32_16x16x32_bf16 v[66:69], v[176:179], v[222:225], v[66:69]
	s_setprio 0
	s_barrier
	s_add_i32 s68, s68, s30
	v_lshl_add_u64 v[142:143], s[26:27], 0, v[0:1]
	s_mov_b32 m0, s68
	ds_read_b128 v[180:183], v146 offset:16384
	ds_read_b128 v[184:187], v146 offset:17408
	ds_read_b128 v[188:191], v146 offset:18432
	ds_read_b128 v[192:195], v146 offset:19456
	ds_read_b128 v[210:213], v146 offset:20480
	ds_read_b128 v[214:217], v146 offset:21504
	ds_read_b128 v[218:221], v146 offset:22528
	ds_read_b128 v[222:225], v146 offset:23552
	global_load_lds_dwordx4 v[142:143], off
	s_add_i32 m0, s68, 0x2000
	s_add_u32 s68, s26, 0x80000
	v_lshl_add_u64 v[240:241], s[26:27], 0, v[130:131]
	s_addc_u32 s69, s27, 0
	s_add_i32 s70, s70, s30
	global_load_lds_dwordx4 v[240:241], off
	v_lshl_add_u64 v[242:243], s[68:69], 0, v[0:1]
	s_mov_b32 m0, s70
	v_lshl_add_u64 v[244:245], s[28:29], 0, v[132:133]
	global_load_lds_dwordx4 v[242:243], off
	v_lshl_add_u64 v[242:243], s[68:69], 0, v[130:131]
	s_add_i32 m0, s70, 0x2000
	s_nop 0
	global_load_lds_dwordx4 v[242:243], off
	v_lshl_add_u64 v[242:243], s[28:29], 0, v[134:135]
	s_waitcnt vmcnt(4)
	s_waitcnt lgkmcnt(0)
	s_barrier
; #define PG8_STAGE(bufoff, gbase, voff) do { _Pragma("unroll") for (int _i = 0; _i < 2; ++_i) \
;         __builtin_amdgcn_global_load_lds((const unsigned*)((const char*)(gbase) + (voff)[_i]), (LAS unsigned*)(lds + (bufoff) + ldsw + _i * 8192), 16, 0, 0); } while (0)
; #define PG8_LDA(dst, b, h) do { _Pragma("unroll") for (int m = 0; m < 4; ++m) _Pragma("unroll") for (int k = 0; k < 2; ++k) dst[m][k] = *(const LAS bf16x8*)(lds + PG8_SA(b, h) + aoff + m * 2048 + k * 1024); } while (0)
; #define PG8_LDB(dst, b, h) do { _Pragma("unroll") for (int n = 0; n < 2; ++n) _Pragma("unroll") for (int k = 0; k < 2; ++k) dst[n][k] = *(const LAS bf16x8*)(lds + PG8_SB(b, h) + boff + n * 2048 + k * 1024); } while (0)
; #define PG8_MMA(ai, bj, At, Bt) do { __builtin_amdgcn_s_setprio(1); _Pragma("unroll") for (int m = 0; m < 4; ++m) _Pragma("unroll") for (int n = 0; n < 2; ++n) _Pragma("unroll") for (int k = 0; k < 2; ++k) \
;         acc[ai][bj][m][n] = __builtin_amdgcn_mfma_f32_16x16x32_bf16(Bt[n][k], At[m][k], acc[ai][bj][m][n], 0, 0, 0); __builtin_amdgcn_s_setprio(0); } while (0)
; #define PG8_WAIT_V(n) asm volatile("s_waitcnt vmcnt(" #n ")" ::: "memory")
; #define PG8_WAIT_L(n) asm volatile("s_waitcnt lgkmcnt(" #n ")" ::: "memory")
; #define PG8_BAR __builtin_amdgcn_s_barrier()
; #define PG8_SCHED __builtin_amdgcn_sched_barrier(0)
; template <class Epi, bool ALIGN_EPI>
; __device__ __forceinline__ void gemm_phase(LAS unsigned char* lds, const int tid, const Gemm g, const StaticOrder& S, const Epi& E) {
;     ...
;             PG8_WAIT_V(8); PG8_WAIT_L(0); PG8_BAR; PG8_MMA(1, 0, At, B0); PG8_MMA(1, 1, At, B1); PG8_BAR; PG8_SCHED;
;             PG8_LDB(B0, 1, 0); PG8_LDB(B1, 1, 1); PG8_SCHED; PG8_LDA(At, 1, 0); PG8_STAGE(PG8_SA(0, 1), a2 + hstepA, voffA);
;             PG8_WAIT_V(8); PG8_WAIT_L(0); PG8_BAR; PG8_MMA(0, 0, At, B0); PG8_MMA(0, 1, At, B1); PG8_BAR; PG8_SCHED;
	s_setprio 1
	s_waitcnt lgkmcnt(0)
	v_mfma_f32_16x16x32_bf16 v[62:65], v[148:151], v[180:183], v[62:65]
	v_mfma_f32_16x16x32_bf16 v[58:61], v[156:159], v[180:183], v[58:61]
	v_mfma_f32_16x16x32_bf16 v[46:49], v[148:151], v[188:191], v[46:49]
	v_mfma_f32_16x16x32_bf16 v[42:45], v[156:159], v[188:191], v[42:45]
	v_mfma_f32_16x16x32_bf16 v[30:33], v[148:151], v[210:213], v[30:33]
	v_mfma_f32_16x16x32_bf16 v[26:29], v[156:159], v[210:213], v[26:29]
	v_mfma_f32_16x16x32_bf16 v[14:17], v[148:151], v[218:221], v[14:17]
	v_mfma_f32_16x16x32_bf16 v[10:13], v[156:159], v[218:221], v[10:13]
	v_mfma_f32_16x16x32_bf16 v[62:65], v[152:155], v[184:187], v[62:65]
	v_mfma_f32_16x16x32_bf16 v[58:61], v[160:163], v[184:187], v[58:61]
	v_mfma_f32_16x16x32_bf16 v[46:49], v[152:155], v[192:195], v[46:49]
	v_mfma_f32_16x16x32_bf16 v[42:45], v[160:163], v[192:195], v[42:45]
	v_mfma_f32_16x16x32_bf16 v[30:33], v[152:155], v[214:217], v[30:33]
	v_mfma_f32_16x16x32_bf16 v[26:29], v[160:163], v[214:217], v[26:29]
	v_mfma_f32_16x16x32_bf16 v[14:17], v[152:155], v[222:225], v[14:17]
	v_mfma_f32_16x16x32_bf16 v[10:13], v[160:163], v[222:225], v[10:13]
	s_setprio 0
	s_setprio 1
	v_mfma_f32_16x16x32_bf16 v[54:57], v[164:167], v[180:183], v[54:57]
	v_mfma_f32_16x16x32_bf16 v[50:53], v[172:175], v[180:183], v[50:53]
	v_mfma_f32_16x16x32_bf16 v[38:41], v[164:167], v[188:191], v[38:41]
	v_mfma_f32_16x16x32_bf16 v[34:37], v[172:175], v[188:191], v[34:37]
	v_mfma_f32_16x16x32_bf16 v[22:25], v[164:167], v[210:213], v[22:25]
	v_mfma_f32_16x16x32_bf16 v[18:21], v[172:175], v[210:213], v[18:21]
	v_mfma_f32_16x16x32_bf16 v[6:9], v[164:167], v[218:221], v[6:9]
	v_mfma_f32_16x16x32_bf16 v[2:5], v[172:175], v[218:221], v[2:5]
	v_mfma_f32_16x16x32_bf16 v[54:57], v[168:171], v[184:187], v[54:57]
	v_mfma_f32_16x16x32_bf16 v[50:53], v[176:179], v[184:187], v[50:53]
	v_mfma_f32_16x16x32_bf16 v[38:41], v[168:171], v[192:195], v[38:41]
	v_mfma_f32_16x16x32_bf16 v[34:37], v[176:179], v[192:195], v[34:37]
	v_mfma_f32_16x16x32_bf16 v[22:25], v[168:171], v[214:217], v[22:25]
	v_mfma_f32_16x16x32_bf16 v[18:21], v[176:179], v[214:217], v[18:21]
	v_mfma_f32_16x16x32_bf16 v[6:9], v[168:171], v[222:225], v[6:9]
	v_mfma_f32_16x16x32_bf16 v[2:5], v[176:179], v[222:225], v[2:5]
	s_setprio 0
	s_barrier
	s_add_i32 s68, 0, 0x18000
	v_add_u32_e32 v147, s68, v145
	s_add_i32 s69, 0, 0x1c000
	ds_read_b128 v[148:151], v147
	ds_read_b128 v[152:155], v147 offset:1024
	ds_read_b128 v[156:159], v147 offset:2048
	ds_read_b128 v[160:163], v147 offset:3072
	v_add_u32_e32 v147, s69, v145
	ds_read_b128 v[164:167], v147
	ds_read_b128 v[168:171], v147 offset:1024
	ds_read_b128 v[172:175], v147 offset:2048
	ds_read_b128 v[176:179], v147 offset:3072
	s_mov_b32 m0, s23
	s_nop 0
	global_load_lds_dwordx4 v[242:243], off
	s_mov_b32 m0, s52
	s_nop 0
	global_load_lds_dwordx4 v[244:245], off
	s_add_u32 s28, s28, 0x80000
	s_addc_u32 s29, s29, 0
	s_mov_b32 m0, s54
	v_lshl_add_u64 v[246:247], s[28:29], 0, v[134:135]
	ds_read_b128 v[180:183], v146 offset:32768
	ds_read_b128 v[184:187], v146 offset:33792
	ds_read_b128 v[188:191], v146 offset:34816
	ds_read_b128 v[192:195], v146 offset:35840
	ds_read_b128 v[210:213], v146 offset:36864
	ds_read_b128 v[214:217], v146 offset:37888
	ds_read_b128 v[218:221], v146 offset:38912
	ds_read_b128 v[222:225], v146 offset:39936
	global_load_lds_dwordx4 v[246:247], off
	v_lshl_add_u64 v[246:247], s[28:29], 0, v[132:133]
	s_mov_b32 m0, s55
	s_nop 0
	global_load_lds_dwordx4 v[246:247], off
	s_waitcnt vmcnt(8)
	s_waitcnt lgkmcnt(0)
	s_barrier
; #define PG8_STAGE(bufoff, gbase, voff) do { _Pragma("unroll") for (int _i = 0; _i < 2; ++_i) \
;         __builtin_amdgcn_global_load_lds((const unsigned*)((const char*)(gbase) + (voff)[_i]), (LAS unsigned*)(lds + (bufoff) + ldsw + _i * 8192), 16, 0, 0); } while (0)
; #define PG8_LDA(dst, b, h) do { _Pragma("unroll") for (int m = 0; m < 4; ++m) _Pragma("unroll") for (int k = 0; k < 2; ++k) dst[m][k] = *(const LAS bf16x8*)(lds + PG8_SA(b, h) + aoff + m * 2048 + k * 1024); } while (0)
; #define PG8_MMA(ai, bj, At, Bt) do { __builtin_amdgcn_s_setprio(1); _Pragma("unroll") for (int m = 0; m < 4; ++m) _Pragma("unroll") for (int n = 0; n < 2; ++n) _Pragma("unroll") for (int k = 0; k < 2; ++k) \
;         acc[ai][bj][m][n] = __builtin_amdgcn_mfma_f32_16x16x32_bf16(Bt[n][k], At[m][k], acc[ai][bj][m][n], 0, 0, 0); __builtin_amdgcn_s_setprio(0); } while (0)
; #define PG8_WAIT_V(n) asm volatile("s_waitcnt vmcnt(" #n ")" ::: "memory")
; #define PG8_WAIT_L(n) asm volatile("s_waitcnt lgkmcnt(" #n ")" ::: "memory")
; #define PG8_BAR __builtin_amdgcn_s_barrier()
; #define PG8_SCHED __builtin_amdgcn_sched_barrier(0)
; template <class Epi, bool ALIGN_EPI>
; __device__ __forceinline__ void gemm_phase(LAS unsigned char* lds, const int tid, const Gemm g, const StaticOrder& S, const Epi& E) {
;     ...
;             PG8_WAIT_V(8); PG8_WAIT_L(0); PG8_BAR; PG8_MMA(0, 0, At, B0); PG8_MMA(0, 1, At, B1); PG8_BAR; PG8_SCHED;
;             PG8_LDA(At, 1, 1); PG8_STAGE(PG8_SB(1, 0), b3, voffB); PG8_STAGE(PG8_SB(1, 1), b3 + hstepB, voffB); PG8_STAGE(PG8_SA(1, 0), a3, voffA);
;             PG8_WAIT_V(8); PG8_WAIT_L(0); PG8_BAR; PG8_MMA(1, 0, At, B0); PG8_MMA(1, 1, At, B1); PG8_BAR; PG8_SCHED;
;         }
;         if constexpr (ALIGN_EPI) { if (wr == 0) PG8_BAR; }
	s_setprio 1
	s_waitcnt lgkmcnt(0)
	v_mfma_f32_16x16x32_bf16 v[126:129], v[148:151], v[180:183], v[126:129]
	v_mfma_f32_16x16x32_bf16 v[122:125], v[156:159], v[180:183], v[122:125]
	v_mfma_f32_16x16x32_bf16 v[110:113], v[148:151], v[188:191], v[110:113]
	v_mfma_f32_16x16x32_bf16 v[106:109], v[156:159], v[188:191], v[106:109]
	v_mfma_f32_16x16x32_bf16 v[94:97], v[148:151], v[210:213], v[94:97]
	v_mfma_f32_16x16x32_bf16 v[90:93], v[156:159], v[210:213], v[90:93]
	v_mfma_f32_16x16x32_bf16 v[78:81], v[148:151], v[218:221], v[78:81]
	v_mfma_f32_16x16x32_bf16 v[74:77], v[156:159], v[218:221], v[74:77]
	v_mfma_f32_16x16x32_bf16 v[126:129], v[152:155], v[184:187], v[126:129]
	v_mfma_f32_16x16x32_bf16 v[122:125], v[160:163], v[184:187], v[122:125]
	v_mfma_f32_16x16x32_bf16 v[110:113], v[152:155], v[192:195], v[110:113]
	v_mfma_f32_16x16x32_bf16 v[106:109], v[160:163], v[192:195], v[106:109]
	v_mfma_f32_16x16x32_bf16 v[94:97], v[152:155], v[214:217], v[94:97]
	v_mfma_f32_16x16x32_bf16 v[90:93], v[160:163], v[214:217], v[90:93]
	v_mfma_f32_16x16x32_bf16 v[78:81], v[152:155], v[222:225], v[78:81]
	v_mfma_f32_16x16x32_bf16 v[74:77], v[160:163], v[222:225], v[74:77]
	s_setprio 0
	s_setprio 1
	v_mfma_f32_16x16x32_bf16 v[118:121], v[164:167], v[180:183], v[118:121]
	v_mfma_f32_16x16x32_bf16 v[114:117], v[172:175], v[180:183], v[114:117]
	v_mfma_f32_16x16x32_bf16 v[102:105], v[164:167], v[188:191], v[102:105]
	v_mfma_f32_16x16x32_bf16 v[98:101], v[172:175], v[188:191], v[98:101]
	v_mfma_f32_16x16x32_bf16 v[86:89], v[164:167], v[210:213], v[86:89]
	v_mfma_f32_16x16x32_bf16 v[82:85], v[172:175], v[210:213], v[82:85]
	v_mfma_f32_16x16x32_bf16 v[70:73], v[164:167], v[218:221], v[70:73]
	v_mfma_f32_16x16x32_bf16 v[66:69], v[172:175], v[218:221], v[66:69]
	v_mfma_f32_16x16x32_bf16 v[118:121], v[168:171], v[184:187], v[118:121]
	v_mfma_f32_16x16x32_bf16 v[114:117], v[176:179], v[184:187], v[114:117]
	v_mfma_f32_16x16x32_bf16 v[102:105], v[168:171], v[192:195], v[102:105]
	v_mfma_f32_16x16x32_bf16 v[98:101], v[176:179], v[192:195], v[98:101]
	v_mfma_f32_16x16x32_bf16 v[86:89], v[168:171], v[214:217], v[86:89]
	v_mfma_f32_16x16x32_bf16 v[82:85], v[176:179], v[214:217], v[82:85]
	v_mfma_f32_16x16x32_bf16 v[70:73], v[168:171], v[222:225], v[70:73]
	v_mfma_f32_16x16x32_bf16 v[66:69], v[176:179], v[222:225], v[66:69]
	s_setprio 0
	s_barrier
	s_add_i32 s28, s68, s30
	v_lshl_add_u64 v[142:143], v[142:143], 0, s[42:43]
	s_mov_b32 m0, s28
	ds_read_b128 v[180:183], v146 offset:49152
	ds_read_b128 v[184:187], v146 offset:50176
	ds_read_b128 v[188:191], v146 offset:51200
	ds_read_b128 v[192:195], v146 offset:52224
	ds_read_b128 v[210:213], v146 offset:53248
	ds_read_b128 v[214:217], v146 offset:54272
	ds_read_b128 v[218:221], v146 offset:55296
	ds_read_b128 v[222:225], v146 offset:56320
	global_load_lds_dwordx4 v[142:143], off
	s_add_i32 m0, s28, 0x2000
	s_add_u32 s26, s26, 0x80080
	v_lshl_add_u64 v[142:143], v[240:241], 0, s[42:43]
	s_addc_u32 s27, s27, 0
	s_add_i32 s28, s69, s30
	global_load_lds_dwordx4 v[142:143], off
	v_lshl_add_u64 v[142:143], s[26:27], 0, v[0:1]
	s_mov_b32 m0, s28
	s_nop 0
	global_load_lds_dwordx4 v[142:143], off
	v_lshl_add_u64 v[142:143], s[26:27], 0, v[130:131]
	s_add_i32 m0, s28, 0x2000
	s_nop 0
	global_load_lds_dwordx4 v[142:143], off
	s_waitcnt vmcnt(4)
	s_waitcnt lgkmcnt(0)
	s_barrier
	s_setprio 1
	s_waitcnt lgkmcnt(0)
	v_mfma_f32_16x16x32_bf16 v[62:65], v[148:151], v[180:183], v[62:65]
	v_mfma_f32_16x16x32_bf16 v[58:61], v[156:159], v[180:183], v[58:61]
	v_mfma_f32_16x16x32_bf16 v[46:49], v[148:151], v[188:191], v[46:49]
	v_mfma_f32_16x16x32_bf16 v[42:45], v[156:159], v[188:191], v[42:45]
	v_mfma_f32_16x16x32_bf16 v[30:33], v[148:151], v[210:213], v[30:33]
	v_mfma_f32_16x16x32_bf16 v[26:29], v[156:159], v[210:213], v[26:29]
	v_mfma_f32_16x16x32_bf16 v[14:17], v[148:151], v[218:221], v[14:17]
	v_mfma_f32_16x16x32_bf16 v[10:13], v[156:159], v[218:221], v[10:13]
	v_mfma_f32_16x16x32_bf16 v[62:65], v[152:155], v[184:187], v[62:65]
	v_mfma_f32_16x16x32_bf16 v[58:61], v[160:163], v[184:187], v[58:61]
	v_mfma_f32_16x16x32_bf16 v[46:49], v[152:155], v[192:195], v[46:49]
	v_mfma_f32_16x16x32_bf16 v[42:45], v[160:163], v[192:195], v[42:45]
	v_mfma_f32_16x16x32_bf16 v[30:33], v[152:155], v[214:217], v[30:33]
	v_mfma_f32_16x16x32_bf16 v[26:29], v[160:163], v[214:217], v[26:29]
	v_mfma_f32_16x16x32_bf16 v[14:17], v[152:155], v[222:225], v[14:17]
	v_mfma_f32_16x16x32_bf16 v[10:13], v[160:163], v[222:225], v[10:13]
	s_setprio 0
	s_setprio 1
	v_mfma_f32_16x16x32_bf16 v[54:57], v[164:167], v[180:183], v[54:57]
	v_mfma_f32_16x16x32_bf16 v[50:53], v[172:175], v[180:183], v[50:53]
	v_mfma_f32_16x16x32_bf16 v[38:41], v[164:167], v[188:191], v[38:41]
	v_mfma_f32_16x16x32_bf16 v[34:37], v[172:175], v[188:191], v[34:37]
	v_mfma_f32_16x16x32_bf16 v[22:25], v[164:167], v[210:213], v[22:25]
	v_mfma_f32_16x16x32_bf16 v[18:21], v[172:175], v[210:213], v[18:21]
	v_mfma_f32_16x16x32_bf16 v[6:9], v[164:167], v[218:221], v[6:9]
	v_mfma_f32_16x16x32_bf16 v[2:5], v[172:175], v[218:221], v[2:5]
	v_mfma_f32_16x16x32_bf16 v[54:57], v[168:171], v[184:187], v[54:57]
	v_mfma_f32_16x16x32_bf16 v[50:53], v[176:179], v[184:187], v[50:53]
	v_mfma_f32_16x16x32_bf16 v[38:41], v[168:171], v[192:195], v[38:41]
	v_mfma_f32_16x16x32_bf16 v[34:37], v[176:179], v[192:195], v[34:37]
	v_mfma_f32_16x16x32_bf16 v[22:25], v[168:171], v[214:217], v[22:25]
	v_mfma_f32_16x16x32_bf16 v[18:21], v[176:179], v[214:217], v[18:21]
	v_mfma_f32_16x16x32_bf16 v[6:9], v[168:171], v[222:225], v[6:9]
	v_mfma_f32_16x16x32_bf16 v[2:5], v[176:179], v[222:225], v[2:5]
	s_setprio 0
	s_barrier
	s_add_i32 s67, s67, 2
	s_add_u32 s15, s15, 0x100
	s_addc_u32 s17, s17, 0
	s_add_u32 s24, s24, 0x100
	s_addc_u32 s25, s25, 0
	s_cmp_gt_u32 s67, 29
	s_cbranch_scc0 .LBB0_143
	s_and_b64 vcc, exec, s[12:13]
	s_cbranch_vccz .LBB0_146
	s_barrier

; #define PG8_STAGE(bufoff, gbase, voff) do { _Pragma("unroll") for (int _i = 0; _i < 2; ++_i) \
;         __builtin_amdgcn_global_load_lds((const unsigned*)((const char*)(gbase) + (voff)[_i]), (LAS unsigned*)(lds + (bufoff) + ldsw + _i * 8192), 16, 0, 0); } while (0)
; #define PG8_LDA(dst, b, h) do { _Pragma("unroll") for (int m = 0; m < 4; ++m) _Pragma("unroll") for (int k = 0; k < 2; ++k) dst[m][k] = *(const LAS bf16x8*)(lds + PG8_SA(b, h) + aoff + m * 2048 + k * 1024); } while (0)
; #define PG8_LDB(dst, b, h) do { _Pragma("unroll") for (int n = 0; n < 2; ++n) _Pragma("unroll") for (int k = 0; k < 2; ++k) dst[n][k] = *(const LAS bf16x8*)(lds + PG8_SB(b, h) + boff + n * 2048 + k * 1024); } while (0)
; #define PG8_MMA(ai, bj, At, Bt) do { __builtin_amdgcn_s_setprio(1); _Pragma("unroll") for (int m = 0; m < 4; ++m) _Pragma("unroll") for (int n = 0; n < 2; ++n) _Pragma("unroll") for (int k = 0; k < 2; ++k) \
;         acc[ai][bj][m][n] = __builtin_amdgcn_mfma_f32_16x16x32_bf16(Bt[n][k], At[m][k], acc[ai][bj][m][n], 0, 0, 0); __builtin_amdgcn_s_setprio(0); } while (0)
; #define PG8_WAIT_V(n) asm volatile("s_waitcnt vmcnt(" #n ")" ::: "memory")
; #define PG8_BAR __builtin_amdgcn_s_barrier()
; template <class Epi, bool ALIGN_EPI>
; __device__ __forceinline__ void gemm_phase(LAS unsigned char* lds, const int tid, const Gemm g, const StaticOrder& S, const Epi& E) {
;     ...
;         for (int t = 0; t < nt; t += 2) {
;             if constexpr (Epi::HOOK) { if (t != 0 && (t & 7) == 0) E.hook(acc, cur, (t >> 3) - 1, wr, wc, fr, fq); }
;             const bool last = (t == nt - 2);
;             const char* a1 = cA + (size_t)(t + 1) * kstepA;
;             const char* a2 = last ? nA : cA + (size_t)(t + 2) * kstepA; const char* b2 = last ? nB : cB + (size_t)(t + 2) * kstepB;
;             const char* a3 = a2 + kstepA; const char* b3 = b2 + kstepB;
;             PG8_LDB(B0, 0, 0); PG8_LDB(B1, 0, 1); PG8_SCHED; PG8_LDA(At, 0, 0); PG8_STAGE(PG8_SA(1, 1), a1 + hstepA, voffA);
;             PG8_WAIT_V(8); PG8_WAIT_L(0); PG8_BAR; PG8_MMA(0, 0, At, B0); PG8_MMA(0, 1, At, B1); PG8_BAR; PG8_SCHED;
;             PG8_LDA(At, 0, 1); PG8_STAGE(PG8_SB(0, 0), b2, voffB); PG8_STAGE(PG8_SB(0, 1), b2 + hstepB, voffB); PG8_STAGE(PG8_SA(0, 0), a2, voffA);
;             PG8_WAIT_V(8); PG8_WAIT_L(0); PG8_BAR; PG8_MMA(1, 0, At, B0); PG8_MMA(1, 1, At, B1); PG8_BAR; PG8_SCHED;
.LBB0_209:
	s_add_i32 s72, s34, 2
	s_add_u32 s35, s30, 0xfff80080
	s_addc_u32 s54, s31, -1
	s_cmp_eq_u32 s21, s34
	s_cselect_b32 s55, s23, s54
	s_cselect_b32 s54, s22, s35
	s_cselect_b32 s35, s25, s71
	s_cselect_b32 s34, s24, s27
	s_add_i32 s73, 0, 0x10000
	s_add_i32 s85, 0, 0x14000
	v_add_u32_e32 v148, s73, v175
	v_add_u32_e32 v164, s85, v175
	ds_read_b128 v[136:139], v148
	ds_read_b128 v[140:143], v148 offset:1024
	ds_read_b128 v[144:147], v148 offset:2048
	ds_read_b128 v[148:151], v148 offset:3072
	ds_read_b128 v[152:155], v164
	ds_read_b128 v[156:159], v164 offset:1024
	ds_read_b128 v[160:163], v164 offset:2048
	ds_read_b128 v[164:167], v164 offset:3072
	v_lshl_add_u64 v[172:173], s[30:31], 0, v[134:135]
	s_add_i32 m0, s58, 0xc000
	ds_read_b128 v[168:171], v177
	ds_read_b128 v[178:181], v177 offset:1024
	ds_read_b128 v[182:185], v177 offset:2048
	ds_read_b128 v[186:189], v177 offset:3072
	ds_read_b128 v[190:193], v177 offset:4096
	ds_read_b128 v[210:213], v177 offset:5120
	ds_read_b128 v[214:217], v177 offset:6144
	ds_read_b128 v[218:221], v177 offset:7168
	global_load_lds_dwordx4 v[172:173], off
	v_lshl_add_u64 v[172:173], s[30:31], 0, v[132:133]
	s_add_i32 m0, s58, 0xe000
	s_nop 0
	global_load_lds_dwordx4 v[172:173], off
	s_sub_u32 s98, s30, 0x80000
	s_subb_u32 s99, s31, 0
	v_lshl_add_u64 v[172:173], s[98:99], 0, v[134:135]
	s_mov_b32 m0, s65
	s_nop 0
	global_load_lds_dwordx4 v[172:173], off
	v_lshl_add_u64 v[172:173], s[98:99], 0, v[132:133]
	s_mov_b32 m0, s66
	s_nop 0
	global_load_lds_dwordx4 v[172:173], off
	s_waitcnt vmcnt(8)
	s_waitcnt lgkmcnt(0)
	s_barrier
	s_setprio 1
	s_waitcnt lgkmcnt(0)
	v_mfma_f32_16x16x32_bf16 v[126:129], v[136:139], v[168:171], v[126:129]
	v_mfma_f32_16x16x32_bf16 v[94:97], v[144:147], v[168:171], v[94:97]
	v_mfma_f32_16x16x32_bf16 v[122:125], v[136:139], v[182:185], v[122:125]
	v_mfma_f32_16x16x32_bf16 v[90:93], v[144:147], v[182:185], v[90:93]
	v_mfma_f32_16x16x32_bf16 v[118:121], v[136:139], v[190:193], v[118:121]
	v_mfma_f32_16x16x32_bf16 v[86:89], v[144:147], v[190:193], v[86:89]
	v_mfma_f32_16x16x32_bf16 v[114:117], v[136:139], v[214:217], v[114:117]
	v_mfma_f32_16x16x32_bf16 v[82:85], v[144:147], v[214:217], v[82:85]
	v_mfma_f32_16x16x32_bf16 v[126:129], v[140:143], v[178:181], v[126:129]
	v_mfma_f32_16x16x32_bf16 v[94:97], v[148:151], v[178:181], v[94:97]
	v_mfma_f32_16x16x32_bf16 v[122:125], v[140:143], v[186:189], v[122:125]
	v_mfma_f32_16x16x32_bf16 v[90:93], v[148:151], v[186:189], v[90:93]
	v_mfma_f32_16x16x32_bf16 v[118:121], v[140:143], v[210:213], v[118:121]
	v_mfma_f32_16x16x32_bf16 v[86:89], v[148:151], v[210:213], v[86:89]
	v_mfma_f32_16x16x32_bf16 v[114:117], v[140:143], v[218:221], v[114:117]
	v_mfma_f32_16x16x32_bf16 v[82:85], v[148:151], v[218:221], v[82:85]
	s_setprio 0
	s_setprio 1
	v_mfma_f32_16x16x32_bf16 v[62:65], v[152:155], v[168:171], v[62:65]
	v_mfma_f32_16x16x32_bf16 v[42:45], v[160:163], v[168:171], v[42:45]
	v_mfma_f32_16x16x32_bf16 v[58:61], v[152:155], v[182:185], v[58:61]
	v_mfma_f32_16x16x32_bf16 v[34:37], v[160:163], v[182:185], v[34:37]
	v_mfma_f32_16x16x32_bf16 v[54:57], v[152:155], v[190:193], v[54:57]
	v_mfma_f32_16x16x32_bf16 v[26:29], v[160:163], v[190:193], v[26:29]
	v_mfma_f32_16x16x32_bf16 v[50:53], v[152:155], v[214:217], v[50:53]
	v_mfma_f32_16x16x32_bf16 v[18:21], v[160:163], v[214:217], v[18:21]
	v_mfma_f32_16x16x32_bf16 v[62:65], v[156:159], v[178:181], v[62:65]
	v_mfma_f32_16x16x32_bf16 v[42:45], v[164:167], v[178:181], v[42:45]
	v_mfma_f32_16x16x32_bf16 v[58:61], v[156:159], v[186:189], v[58:61]
	v_mfma_f32_16x16x32_bf16 v[34:37], v[164:167], v[186:189], v[34:37]
	v_mfma_f32_16x16x32_bf16 v[54:57], v[156:159], v[210:213], v[54:57]
	v_mfma_f32_16x16x32_bf16 v[26:29], v[164:167], v[210:213], v[26:29]
	v_mfma_f32_16x16x32_bf16 v[50:53], v[156:159], v[218:221], v[50:53]
	v_mfma_f32_16x16x32_bf16 v[18:21], v[164:167], v[218:221], v[18:21]
	s_setprio 0
	s_barrier
	s_add_i32 s73, s73, s56
	v_lshl_add_u64 v[172:173], s[34:35], 0, v[0:1]
	s_mov_b32 m0, s73
	ds_read_b128 v[168:171], v177 offset:16384
	ds_read_b128 v[178:181], v177 offset:17408
	ds_read_b128 v[182:185], v177 offset:18432
	ds_read_b128 v[186:189], v177 offset:19456
	ds_read_b128 v[190:193], v177 offset:20480
	ds_read_b128 v[210:213], v177 offset:21504
	ds_read_b128 v[214:217], v177 offset:22528
	ds_read_b128 v[218:221], v177 offset:23552
	global_load_lds_dwordx4 v[172:173], off
	s_add_i32 m0, s73, 0x2000
	s_add_u32 s90, s34, 0x80000
	v_lshl_add_u64 v[194:195], s[34:35], 0, v[130:131]
	s_addc_u32 s91, s35, 0
	s_add_i32 s73, s85, s56
	global_load_lds_dwordx4 v[194:195], off
	v_lshl_add_u64 v[222:223], s[90:91], 0, v[0:1]
	s_mov_b32 m0, s73
	v_lshl_add_u64 v[224:225], s[54:55], 0, v[130:131]
	global_load_lds_dwordx4 v[222:223], off
	v_lshl_add_u64 v[222:223], s[90:91], 0, v[130:131]
	s_add_i32 m0, s73, 0x2000
	s_nop 0
	global_load_lds_dwordx4 v[222:223], off
	v_lshl_add_u64 v[222:223], s[54:55], 0, v[0:1]
	s_waitcnt vmcnt(4)
	s_waitcnt lgkmcnt(0)
	s_barrier
; #define PG8_STAGE(bufoff, gbase, voff) do { _Pragma("unroll") for (int _i = 0; _i < 2; ++_i) \
;         __builtin_amdgcn_global_load_lds((const unsigned*)((const char*)(gbase) + (voff)[_i]), (LAS unsigned*)(lds + (bufoff) + ldsw + _i * 8192), 16, 0, 0); } while (0)
; #define PG8_LDA(dst, b, h) do { _Pragma("unroll") for (int m = 0; m < 4; ++m) _Pragma("unroll") for (int k = 0; k < 2; ++k) dst[m][k] = *(const LAS bf16x8*)(lds + PG8_SA(b, h) + aoff + m * 2048 + k * 1024); } while (0)
; #define PG8_LDB(dst, b, h) do { _Pragma("unroll") for (int n = 0; n < 2; ++n) _Pragma("unroll") for (int k = 0; k < 2; ++k) dst[n][k] = *(const LAS bf16x8*)(lds + PG8_SB(b, h) + boff + n * 2048 + k * 1024); } while (0)
; #define PG8_MMA(ai, bj, At, Bt) do { __builtin_amdgcn_s_setprio(1); _Pragma("unroll") for (int m = 0; m < 4; ++m) _Pragma("unroll") for (int n = 0; n < 2; ++n) _Pragma("unroll") for (int k = 0; k < 2; ++k) \
;         acc[ai][bj][m][n] = __builtin_amdgcn_mfma_f32_16x16x32_bf16(Bt[n][k], At[m][k], acc[ai][bj][m][n], 0, 0, 0); __builtin_amdgcn_s_setprio(0); } while (0)
; #define PG8_WAIT_V(n) asm volatile("s_waitcnt vmcnt(" #n ")" ::: "memory")
; #define PG8_WAIT_L(n) asm volatile("s_waitcnt lgkmcnt(" #n ")" ::: "memory")
; #define PG8_BAR __builtin_amdgcn_s_barrier()
; #define PG8_SCHED __builtin_amdgcn_sched_barrier(0)
; template <class Epi, bool ALIGN_EPI>
; __device__ __forceinline__ void gemm_phase(LAS unsigned char* lds, const int tid, const Gemm g, const StaticOrder& S, const Epi& E) {
;     ...
;             PG8_WAIT_V(8); PG8_WAIT_L(0); PG8_BAR; PG8_MMA(1, 0, At, B0); PG8_MMA(1, 1, At, B1); PG8_BAR; PG8_SCHED;
;             PG8_LDB(B0, 1, 0); PG8_LDB(B1, 1, 1); PG8_SCHED; PG8_LDA(At, 1, 0); PG8_STAGE(PG8_SA(0, 1), a2 + hstepA, voffA);
;             PG8_WAIT_V(8); PG8_WAIT_L(0); PG8_BAR; PG8_MMA(0, 0, At, B0); PG8_MMA(0, 1, At, B1); PG8_BAR; PG8_SCHED;
	s_setprio 1
	s_waitcnt lgkmcnt(0)
	v_mfma_f32_16x16x32_bf16 v[110:113], v[136:139], v[168:171], v[110:113]
	v_mfma_f32_16x16x32_bf16 v[78:81], v[144:147], v[168:171], v[78:81]
	v_mfma_f32_16x16x32_bf16 v[106:109], v[136:139], v[182:185], v[106:109]
	v_mfma_f32_16x16x32_bf16 v[74:77], v[144:147], v[182:185], v[74:77]
	v_mfma_f32_16x16x32_bf16 v[102:105], v[136:139], v[190:193], v[102:105]
	v_mfma_f32_16x16x32_bf16 v[70:73], v[144:147], v[190:193], v[70:73]
	v_mfma_f32_16x16x32_bf16 v[98:101], v[136:139], v[214:217], v[98:101]
	v_mfma_f32_16x16x32_bf16 v[66:69], v[144:147], v[214:217], v[66:69]
	v_mfma_f32_16x16x32_bf16 v[110:113], v[140:143], v[178:181], v[110:113]
	v_mfma_f32_16x16x32_bf16 v[78:81], v[148:151], v[178:181], v[78:81]
	v_mfma_f32_16x16x32_bf16 v[106:109], v[140:143], v[186:189], v[106:109]
	v_mfma_f32_16x16x32_bf16 v[74:77], v[148:151], v[186:189], v[74:77]
	v_mfma_f32_16x16x32_bf16 v[102:105], v[140:143], v[210:213], v[102:105]
	v_mfma_f32_16x16x32_bf16 v[70:73], v[148:151], v[210:213], v[70:73]
	v_mfma_f32_16x16x32_bf16 v[98:101], v[140:143], v[218:221], v[98:101]
	v_mfma_f32_16x16x32_bf16 v[66:69], v[148:151], v[218:221], v[66:69]
	s_setprio 0
	s_setprio 1
	v_mfma_f32_16x16x32_bf16 v[46:49], v[152:155], v[168:171], v[46:49]
	v_mfma_f32_16x16x32_bf16 v[14:17], v[160:163], v[168:171], v[14:17]
	v_mfma_f32_16x16x32_bf16 v[38:41], v[152:155], v[182:185], v[38:41]
	v_mfma_f32_16x16x32_bf16 v[10:13], v[160:163], v[182:185], v[10:13]
	v_mfma_f32_16x16x32_bf16 v[30:33], v[152:155], v[190:193], v[30:33]
	v_mfma_f32_16x16x32_bf16 v[6:9], v[160:163], v[190:193], v[6:9]
	v_mfma_f32_16x16x32_bf16 v[22:25], v[152:155], v[214:217], v[22:25]
	v_mfma_f32_16x16x32_bf16 v[2:5], v[160:163], v[214:217], v[2:5]
	v_mfma_f32_16x16x32_bf16 v[46:49], v[156:159], v[178:181], v[46:49]
	v_mfma_f32_16x16x32_bf16 v[14:17], v[164:167], v[178:181], v[14:17]
	v_mfma_f32_16x16x32_bf16 v[38:41], v[156:159], v[186:189], v[38:41]
	v_mfma_f32_16x16x32_bf16 v[10:13], v[164:167], v[186:189], v[10:13]
	v_mfma_f32_16x16x32_bf16 v[30:33], v[156:159], v[210:213], v[30:33]
	v_mfma_f32_16x16x32_bf16 v[6:9], v[164:167], v[210:213], v[6:9]
	v_mfma_f32_16x16x32_bf16 v[22:25], v[156:159], v[218:221], v[22:25]
	v_mfma_f32_16x16x32_bf16 v[2:5], v[164:167], v[218:221], v[2:5]
	s_setprio 0
	s_barrier
	s_add_i32 s73, 0, 0x18000
	s_add_i32 s85, 0, 0x1c000
	v_add_u32_e32 v148, s73, v175
	v_add_u32_e32 v164, s85, v175
	ds_read_b128 v[136:139], v148
	ds_read_b128 v[140:143], v148 offset:1024
	ds_read_b128 v[144:147], v148 offset:2048
	ds_read_b128 v[148:151], v148 offset:3072
	ds_read_b128 v[152:155], v164
	ds_read_b128 v[156:159], v164 offset:1024
	ds_read_b128 v[160:163], v164 offset:2048
	ds_read_b128 v[164:167], v164 offset:3072
	s_mov_b32 m0, s58
	s_nop 0
	global_load_lds_dwordx4 v[222:223], off
	s_mov_b32 m0, s60
	s_nop 0
	global_load_lds_dwordx4 v[224:225], off
	s_add_u32 s54, s54, 0x80000
	s_addc_u32 s55, s55, 0
	s_mov_b32 m0, s61
	v_lshl_add_u64 v[240:241], s[54:55], 0, v[0:1]
	ds_read_b128 v[168:171], v177 offset:32768
	ds_read_b128 v[178:181], v177 offset:33792
	ds_read_b128 v[182:185], v177 offset:34816
	ds_read_b128 v[186:189], v177 offset:35840
	ds_read_b128 v[190:193], v177 offset:36864
	ds_read_b128 v[210:213], v177 offset:37888
	ds_read_b128 v[214:217], v177 offset:38912
	ds_read_b128 v[218:221], v177 offset:39936
	global_load_lds_dwordx4 v[240:241], off
	v_lshl_add_u64 v[240:241], s[54:55], 0, v[130:131]
	s_mov_b32 m0, s62
	s_nop 0
	global_load_lds_dwordx4 v[240:241], off
	s_waitcnt vmcnt(8)
	s_waitcnt lgkmcnt(0)
	s_barrier
; #define PG8_STAGE(bufoff, gbase, voff) do { _Pragma("unroll") for (int _i = 0; _i < 2; ++_i) \
;         __builtin_amdgcn_global_load_lds((const unsigned*)((const char*)(gbase) + (voff)[_i]), (LAS unsigned*)(lds + (bufoff) + ldsw + _i * 8192), 16, 0, 0); } while (0)
; #define PG8_LDA(dst, b, h) do { _Pragma("unroll") for (int m = 0; m < 4; ++m) _Pragma("unroll") for (int k = 0; k < 2; ++k) dst[m][k] = *(const LAS bf16x8*)(lds + PG8_SA(b, h) + aoff + m * 2048 + k * 1024); } while (0)
; #define PG8_MMA(ai, bj, At, Bt) do { __builtin_amdgcn_s_setprio(1); _Pragma("unroll") for (int m = 0; m < 4; ++m) _Pragma("unroll") for (int n = 0; n < 2; ++n) _Pragma("unroll") for (int k = 0; k < 2; ++k) \
;         acc[ai][bj][m][n] = __builtin_amdgcn_mfma_f32_16x16x32_bf16(Bt[n][k], At[m][k], acc[ai][bj][m][n], 0, 0, 0); __builtin_amdgcn_s_setprio(0); } while (0)
; #define PG8_WAIT_V(n) asm volatile("s_waitcnt vmcnt(" #n ")" ::: "memory")
; #define PG8_WAIT_L(n) asm volatile("s_waitcnt lgkmcnt(" #n ")" ::: "memory")
; #define PG8_BAR __builtin_amdgcn_s_barrier()
; #define PG8_SCHED __builtin_amdgcn_sched_barrier(0)
; template <class Epi, bool ALIGN_EPI>
; __device__ __forceinline__ void gemm_phase(LAS unsigned char* lds, const int tid, const Gemm g, const StaticOrder& S, const Epi& E) {
;     ...
;             PG8_WAIT_V(8); PG8_WAIT_L(0); PG8_BAR; PG8_MMA(0, 0, At, B0); PG8_MMA(0, 1, At, B1); PG8_BAR; PG8_SCHED;
;             PG8_LDA(At, 1, 1); PG8_STAGE(PG8_SB(1, 0), b3, voffB); PG8_STAGE(PG8_SB(1, 1), b3 + hstepB, voffB); PG8_STAGE(PG8_SA(1, 0), a3, voffA);
;             PG8_WAIT_V(8); PG8_WAIT_L(0); PG8_BAR; PG8_MMA(1, 0, At, B0); PG8_MMA(1, 1, At, B1); PG8_BAR; PG8_SCHED;
;         }
;         if constexpr (ALIGN_EPI) { if (wr == 0) PG8_BAR; }
	s_setprio 1
	s_waitcnt lgkmcnt(0)
	v_mfma_f32_16x16x32_bf16 v[126:129], v[136:139], v[168:171], v[126:129]
	v_mfma_f32_16x16x32_bf16 v[94:97], v[144:147], v[168:171], v[94:97]
	v_mfma_f32_16x16x32_bf16 v[122:125], v[136:139], v[182:185], v[122:125]
	v_mfma_f32_16x16x32_bf16 v[90:93], v[144:147], v[182:185], v[90:93]
	v_mfma_f32_16x16x32_bf16 v[118:121], v[136:139], v[190:193], v[118:121]
	v_mfma_f32_16x16x32_bf16 v[86:89], v[144:147], v[190:193], v[86:89]
	v_mfma_f32_16x16x32_bf16 v[114:117], v[136:139], v[214:217], v[114:117]
	v_mfma_f32_16x16x32_bf16 v[82:85], v[144:147], v[214:217], v[82:85]
	v_mfma_f32_16x16x32_bf16 v[126:129], v[140:143], v[178:181], v[126:129]
	v_mfma_f32_16x16x32_bf16 v[94:97], v[148:151], v[178:181], v[94:97]
	v_mfma_f32_16x16x32_bf16 v[122:125], v[140:143], v[186:189], v[122:125]
	v_mfma_f32_16x16x32_bf16 v[90:93], v[148:151], v[186:189], v[90:93]
	v_mfma_f32_16x16x32_bf16 v[118:121], v[140:143], v[210:213], v[118:121]
	v_mfma_f32_16x16x32_bf16 v[86:89], v[148:151], v[210:213], v[86:89]
	v_mfma_f32_16x16x32_bf16 v[114:117], v[140:143], v[218:221], v[114:117]
	v_mfma_f32_16x16x32_bf16 v[82:85], v[148:151], v[218:221], v[82:85]
	s_setprio 0
	s_setprio 1
	v_mfma_f32_16x16x32_bf16 v[62:65], v[152:155], v[168:171], v[62:65]
	v_mfma_f32_16x16x32_bf16 v[42:45], v[160:163], v[168:171], v[42:45]
	v_mfma_f32_16x16x32_bf16 v[58:61], v[152:155], v[182:185], v[58:61]
	v_mfma_f32_16x16x32_bf16 v[34:37], v[160:163], v[182:185], v[34:37]
	v_mfma_f32_16x16x32_bf16 v[54:57], v[152:155], v[190:193], v[54:57]
	v_mfma_f32_16x16x32_bf16 v[26:29], v[160:163], v[190:193], v[26:29]
	v_mfma_f32_16x16x32_bf16 v[50:53], v[152:155], v[214:217], v[50:53]
	v_mfma_f32_16x16x32_bf16 v[18:21], v[160:163], v[214:217], v[18:21]
	v_mfma_f32_16x16x32_bf16 v[62:65], v[156:159], v[178:181], v[62:65]
	v_mfma_f32_16x16x32_bf16 v[42:45], v[164:167], v[178:181], v[42:45]
	v_mfma_f32_16x16x32_bf16 v[58:61], v[156:159], v[186:189], v[58:61]
	v_mfma_f32_16x16x32_bf16 v[34:37], v[164:167], v[186:189], v[34:37]
	v_mfma_f32_16x16x32_bf16 v[54:57], v[156:159], v[210:213], v[54:57]
	v_mfma_f32_16x16x32_bf16 v[26:29], v[164:167], v[210:213], v[26:29]
	v_mfma_f32_16x16x32_bf16 v[50:53], v[156:159], v[218:221], v[50:53]
	v_mfma_f32_16x16x32_bf16 v[18:21], v[164:167], v[218:221], v[18:21]
	s_setprio 0
	s_barrier
	s_add_i32 s54, s73, s56
	v_lshl_add_u64 v[172:173], v[172:173], 0, s[42:43]
	s_mov_b32 m0, s54
	ds_read_b128 v[168:171], v177 offset:49152
	ds_read_b128 v[178:181], v177 offset:50176
	ds_read_b128 v[182:185], v177 offset:51200
	ds_read_b128 v[186:189], v177 offset:52224
	ds_read_b128 v[190:193], v177 offset:53248
	ds_read_b128 v[210:213], v177 offset:54272
	ds_read_b128 v[214:217], v177 offset:55296
	ds_read_b128 v[218:221], v177 offset:56320
	global_load_lds_dwordx4 v[172:173], off
	s_add_i32 m0, s54, 0x2000
	s_add_u32 s34, s34, 0x80080
	v_lshl_add_u64 v[172:173], v[194:195], 0, s[42:43]
	s_addc_u32 s35, s35, 0
	s_add_i32 s54, s85, s56
	global_load_lds_dwordx4 v[172:173], off
	v_lshl_add_u64 v[172:173], s[34:35], 0, v[0:1]
	s_mov_b32 m0, s54
	s_nop 0
	global_load_lds_dwordx4 v[172:173], off
	v_lshl_add_u64 v[172:173], s[34:35], 0, v[130:131]
	s_add_i32 m0, s54, 0x2000
	s_nop 0
	global_load_lds_dwordx4 v[172:173], off
	s_waitcnt vmcnt(4)
	s_waitcnt lgkmcnt(0)
	s_barrier
	s_setprio 1
	s_waitcnt lgkmcnt(0)
	v_mfma_f32_16x16x32_bf16 v[110:113], v[136:139], v[168:171], v[110:113]
	v_mfma_f32_16x16x32_bf16 v[78:81], v[144:147], v[168:171], v[78:81]
	v_mfma_f32_16x16x32_bf16 v[106:109], v[136:139], v[182:185], v[106:109]
	v_mfma_f32_16x16x32_bf16 v[74:77], v[144:147], v[182:185], v[74:77]
	v_mfma_f32_16x16x32_bf16 v[102:105], v[136:139], v[190:193], v[102:105]
	v_mfma_f32_16x16x32_bf16 v[70:73], v[144:147], v[190:193], v[70:73]
	v_mfma_f32_16x16x32_bf16 v[98:101], v[136:139], v[214:217], v[98:101]
	v_mfma_f32_16x16x32_bf16 v[66:69], v[144:147], v[214:217], v[66:69]
	v_mfma_f32_16x16x32_bf16 v[110:113], v[140:143], v[178:181], v[110:113]
	v_mfma_f32_16x16x32_bf16 v[78:81], v[148:151], v[178:181], v[78:81]
	v_mfma_f32_16x16x32_bf16 v[106:109], v[140:143], v[186:189], v[106:109]
	v_mfma_f32_16x16x32_bf16 v[74:77], v[148:151], v[186:189], v[74:77]
	v_mfma_f32_16x16x32_bf16 v[102:105], v[140:143], v[210:213], v[102:105]
	v_mfma_f32_16x16x32_bf16 v[70:73], v[148:151], v[210:213], v[70:73]
	v_mfma_f32_16x16x32_bf16 v[98:101], v[140:143], v[218:221], v[98:101]
	v_mfma_f32_16x16x32_bf16 v[66:69], v[148:151], v[218:221], v[66:69]
	s_setprio 0
	s_setprio 1
	v_mfma_f32_16x16x32_bf16 v[46:49], v[152:155], v[168:171], v[46:49]
	v_mfma_f32_16x16x32_bf16 v[14:17], v[160:163], v[168:171], v[14:17]
	v_mfma_f32_16x16x32_bf16 v[38:41], v[152:155], v[182:185], v[38:41]
	v_mfma_f32_16x16x32_bf16 v[10:13], v[160:163], v[182:185], v[10:13]
	v_mfma_f32_16x16x32_bf16 v[30:33], v[152:155], v[190:193], v[30:33]
	v_mfma_f32_16x16x32_bf16 v[6:9], v[160:163], v[190:193], v[6:9]
	v_mfma_f32_16x16x32_bf16 v[22:25], v[152:155], v[214:217], v[22:25]
	v_mfma_f32_16x16x32_bf16 v[2:5], v[160:163], v[214:217], v[2:5]
	v_mfma_f32_16x16x32_bf16 v[46:49], v[156:159], v[178:181], v[46:49]
	v_mfma_f32_16x16x32_bf16 v[14:17], v[164:167], v[178:181], v[14:17]
	v_mfma_f32_16x16x32_bf16 v[38:41], v[156:159], v[186:189], v[38:41]
	v_mfma_f32_16x16x32_bf16 v[10:13], v[164:167], v[186:189], v[10:13]
	v_mfma_f32_16x16x32_bf16 v[30:33], v[156:159], v[210:213], v[30:33]
	v_mfma_f32_16x16x32_bf16 v[6:9], v[164:167], v[210:213], v[6:9]
	v_mfma_f32_16x16x32_bf16 v[22:25], v[156:159], v[218:221], v[22:25]
	v_mfma_f32_16x16x32_bf16 v[2:5], v[164:167], v[218:221], v[2:5]
	s_setprio 0
	s_barrier
	s_add_u32 s27, s27, 0x100
	s_addc_u32 s71, s71, 0
	s_add_u32 s30, s30, 0x100
	s_addc_u32 s31, s31, 0
	s_cmp_ge_u32 s72, s19
	s_mov_b32 s34, s72
	s_cbranch_scc0 .LBB0_209
	s_and_b64 vcc, exec, s[16:17]
	s_cbranch_vccz .LBB0_212
	s_barrier

; #define PG8_STAGE(bufoff, gbase, voff) do { _Pragma("unroll") for (int _i = 0; _i < 2; ++_i) \
;         __builtin_amdgcn_global_load_lds((const unsigned*)((const char*)(gbase) + (voff)[_i]), (LAS unsigned*)(lds + (bufoff) + ldsw + _i * 8192), 16, 0, 0); } while (0)
; #define PG8_LDA(dst, b, h) do { _Pragma("unroll") for (int m = 0; m < 4; ++m) _Pragma("unroll") for (int k = 0; k < 2; ++k) dst[m][k] = *(const LAS bf16x8*)(lds + PG8_SA(b, h) + aoff + m * 2048 + k * 1024); } while (0)
; #define PG8_LDB(dst, b, h) do { _Pragma("unroll") for (int n = 0; n < 2; ++n) _Pragma("unroll") for (int k = 0; k < 2; ++k) dst[n][k] = *(const LAS bf16x8*)(lds + PG8_SB(b, h) + boff + n * 2048 + k * 1024); } while (0)
; #define PG8_MMA(ai, bj, At, Bt) do { __builtin_amdgcn_s_setprio(1); _Pragma("unroll") for (int m = 0; m < 4; ++m) _Pragma("unroll") for (int n = 0; n < 2; ++n) _Pragma("unroll") for (int k = 0; k < 2; ++k) \
;         acc[ai][bj][m][n] = __builtin_amdgcn_mfma_f32_16x16x32_bf16(Bt[n][k], At[m][k], acc[ai][bj][m][n], 0, 0, 0); __builtin_amdgcn_s_setprio(0); } while (0)
; #define PG8_WAIT_V(n) asm volatile("s_waitcnt vmcnt(" #n ")" ::: "memory")
; #define PG8_BAR __builtin_amdgcn_s_barrier()
; template <class Epi, bool ALIGN_EPI>
; __device__ __forceinline__ void gemm_phase(LAS unsigned char* lds, const int tid, const Gemm g, const StaticOrder& S, const Epi& E) {
;     ...
;         for (int t = 0; t < nt; t += 2) {
;             if constexpr (Epi::HOOK) { if (t != 0 && (t & 7) == 0) E.hook(acc, cur, (t >> 3) - 1, wr, wc, fr, fq); }
;             const bool last = (t == nt - 2);
;             const char* a1 = cA + (size_t)(t + 1) * kstepA;
;             const char* a2 = last ? nA : cA + (size_t)(t + 2) * kstepA; const char* b2 = last ? nB : cB + (size_t)(t + 2) * kstepB;
;             const char* a3 = a2 + kstepA; const char* b3 = b2 + kstepB;
;             PG8_LDB(B0, 0, 0); PG8_LDB(B1, 0, 1); PG8_SCHED; PG8_LDA(At, 0, 0); PG8_STAGE(PG8_SA(1, 1), a1 + hstepA, voffA);
;             PG8_WAIT_V(8); PG8_WAIT_L(0); PG8_BAR; PG8_MMA(0, 0, At, B0); PG8_MMA(0, 1, At, B1); PG8_BAR; PG8_SCHED;
;             PG8_LDA(At, 0, 1); PG8_STAGE(PG8_SB(0, 0), b2, voffB); PG8_STAGE(PG8_SB(0, 1), b2 + hstepB, voffB); PG8_STAGE(PG8_SA(0, 0), a2, voffA);
;             PG8_WAIT_V(8); PG8_WAIT_L(0); PG8_BAR; PG8_MMA(1, 0, At, B0); PG8_MMA(1, 1, At, B1); PG8_BAR; PG8_SCHED;
.LBB0_263:
	s_add_i32 s5, s5, 2
	s_add_u32 s34, s30, 0xfff80080
	s_addc_u32 s35, s31, -1
	s_add_i32 s94, 0, 0x10000
	s_cmp_eq_u32 s91, s92
	s_cselect_b32 s55, s23, s35
	s_cselect_b32 s54, s22, s34
	v_add_u32_e32 v0, s94, v205
	s_cselect_b32 s35, s25, s36
	s_cselect_b32 s34, s24, s21
	s_add_i32 s96, 0, 0x14000
	ds_read_b128 v[132:135], v0
	ds_read_b128 v[136:139], v0 offset:1024
	ds_read_b128 v[140:143], v0 offset:2048
	ds_read_b128 v[144:147], v0 offset:3072
	v_add_u32_e32 v0, s96, v205
	ds_read_b128 v[148:151], v0
	ds_read_b128 v[152:155], v0 offset:1024
	ds_read_b128 v[156:159], v0 offset:2048
	ds_read_b128 v[160:163], v0 offset:3072
	v_lshl_add_u64 v[2:3], s[30:31], 0, v[220:221]
	s_add_i32 m0, s68, 0xc000
	ds_read_b128 v[164:167], v209
	ds_read_b128 v[168:171], v209 offset:1024
	ds_read_b128 v[172:175], v209 offset:2048
	ds_read_b128 v[176:179], v209 offset:3072
	ds_read_b128 v[180:183], v209 offset:4096
	ds_read_b128 v[184:187], v209 offset:5120
	ds_read_b128 v[188:191], v209 offset:6144
	ds_read_b128 v[192:195], v209 offset:7168
	global_load_lds_dwordx4 v[2:3], off
	v_lshl_add_u64 v[2:3], s[30:31], 0, v[218:219]
	s_add_i32 m0, s68, 0xe000
	s_nop 0
	global_load_lds_dwordx4 v[2:3], off
	s_sub_u32 s98, s30, 0x80000
	s_subb_u32 s99, s31, 0
	v_lshl_add_u64 v[2:3], s[98:99], 0, v[220:221]
	s_mov_b32 m0, s72
	s_nop 0
	global_load_lds_dwordx4 v[2:3], off
	v_lshl_add_u64 v[2:3], s[98:99], 0, v[218:219]
	s_mov_b32 m0, s73
	s_nop 0
	global_load_lds_dwordx4 v[2:3], off
	s_waitcnt vmcnt(8)
	s_waitcnt lgkmcnt(0)
	s_barrier
	s_setprio 1
	s_waitcnt lgkmcnt(0)
	v_mfma_f32_16x16x32_bf16 v[128:131], v[132:135], v[164:167], v[128:131]
	v_mfma_f32_16x16x32_bf16 v[124:127], v[140:143], v[164:167], v[124:127]
	v_mfma_f32_16x16x32_bf16 v[112:115], v[132:135], v[172:175], v[112:115]
	v_mfma_f32_16x16x32_bf16 v[108:111], v[140:143], v[172:175], v[108:111]
	v_mfma_f32_16x16x32_bf16 v[96:99], v[132:135], v[180:183], v[96:99]
	v_mfma_f32_16x16x32_bf16 v[92:95], v[140:143], v[180:183], v[92:95]
	v_mfma_f32_16x16x32_bf16 v[80:83], v[132:135], v[188:191], v[80:83]
	v_mfma_f32_16x16x32_bf16 v[76:79], v[140:143], v[188:191], v[76:79]
	v_mfma_f32_16x16x32_bf16 v[128:131], v[136:139], v[168:171], v[128:131]
	v_mfma_f32_16x16x32_bf16 v[124:127], v[144:147], v[168:171], v[124:127]
	v_mfma_f32_16x16x32_bf16 v[112:115], v[136:139], v[176:179], v[112:115]
	v_mfma_f32_16x16x32_bf16 v[108:111], v[144:147], v[176:179], v[108:111]
	v_mfma_f32_16x16x32_bf16 v[96:99], v[136:139], v[184:187], v[96:99]
	v_mfma_f32_16x16x32_bf16 v[92:95], v[144:147], v[184:187], v[92:95]
	v_mfma_f32_16x16x32_bf16 v[80:83], v[136:139], v[192:195], v[80:83]
	v_mfma_f32_16x16x32_bf16 v[76:79], v[144:147], v[192:195], v[76:79]
	s_setprio 0
	s_setprio 1
	v_mfma_f32_16x16x32_bf16 v[120:123], v[148:151], v[164:167], v[120:123]
	v_mfma_f32_16x16x32_bf16 v[116:119], v[156:159], v[164:167], v[116:119]
	v_mfma_f32_16x16x32_bf16 v[104:107], v[148:151], v[172:175], v[104:107]
	v_mfma_f32_16x16x32_bf16 v[100:103], v[156:159], v[172:175], v[100:103]
	v_mfma_f32_16x16x32_bf16 v[88:91], v[148:151], v[180:183], v[88:91]
	v_mfma_f32_16x16x32_bf16 v[84:87], v[156:159], v[180:183], v[84:87]
	v_mfma_f32_16x16x32_bf16 v[72:75], v[148:151], v[188:191], v[72:75]
	v_mfma_f32_16x16x32_bf16 v[68:71], v[156:159], v[188:191], v[68:71]
	v_mfma_f32_16x16x32_bf16 v[120:123], v[152:155], v[168:171], v[120:123]
	v_mfma_f32_16x16x32_bf16 v[116:119], v[160:163], v[168:171], v[116:119]
	v_mfma_f32_16x16x32_bf16 v[104:107], v[152:155], v[176:179], v[104:107]
	v_mfma_f32_16x16x32_bf16 v[100:103], v[160:163], v[176:179], v[100:103]
	v_mfma_f32_16x16x32_bf16 v[88:91], v[152:155], v[184:187], v[88:91]
	v_mfma_f32_16x16x32_bf16 v[84:87], v[160:163], v[184:187], v[84:87]
	v_mfma_f32_16x16x32_bf16 v[72:75], v[152:155], v[192:195], v[72:75]
	v_mfma_f32_16x16x32_bf16 v[68:71], v[160:163], v[192:195], v[68:71]
	s_setprio 0
	s_barrier
	s_add_i32 s94, s94, s67
	v_lshl_add_u64 v[240:241], s[34:35], 0, v[212:213]
	s_mov_b32 m0, s94
	ds_read_b128 v[164:167], v209 offset:16384
	ds_read_b128 v[168:171], v209 offset:17408
	ds_read_b128 v[172:175], v209 offset:18432
	ds_read_b128 v[176:179], v209 offset:19456
	ds_read_b128 v[180:183], v209 offset:20480
	ds_read_b128 v[184:187], v209 offset:21504
	ds_read_b128 v[188:191], v209 offset:22528
	ds_read_b128 v[192:195], v209 offset:23552
	global_load_lds_dwordx4 v[240:241], off
	s_add_i32 m0, s94, 0x2000
	s_add_u32 s94, s34, 0x80000
	v_lshl_add_u64 v[242:243], s[34:35], 0, v[216:217]
	s_addc_u32 s95, s35, 0
	s_add_i32 s96, s96, s67
	global_load_lds_dwordx4 v[242:243], off
	v_lshl_add_u64 v[2:3], s[94:95], 0, v[212:213]
	s_mov_b32 m0, s96
	v_lshl_add_u64 v[244:245], s[54:55], 0, v[210:211]
	global_load_lds_dwordx4 v[2:3], off
	v_lshl_add_u64 v[2:3], s[94:95], 0, v[216:217]
	s_add_i32 m0, s96, 0x2000
	v_lshl_add_u64 v[246:247], s[54:55], 0, v[214:215]
	global_load_lds_dwordx4 v[2:3], off
	s_waitcnt vmcnt(4)
	s_waitcnt lgkmcnt(0)
	s_barrier
; #define PG8_STAGE(bufoff, gbase, voff) do { _Pragma("unroll") for (int _i = 0; _i < 2; ++_i) \
;         __builtin_amdgcn_global_load_lds((const unsigned*)((const char*)(gbase) + (voff)[_i]), (LAS unsigned*)(lds + (bufoff) + ldsw + _i * 8192), 16, 0, 0); } while (0)
; #define PG8_LDA(dst, b, h) do { _Pragma("unroll") for (int m = 0; m < 4; ++m) _Pragma("unroll") for (int k = 0; k < 2; ++k) dst[m][k] = *(const LAS bf16x8*)(lds + PG8_SA(b, h) + aoff + m * 2048 + k * 1024); } while (0)
; #define PG8_LDB(dst, b, h) do { _Pragma("unroll") for (int n = 0; n < 2; ++n) _Pragma("unroll") for (int k = 0; k < 2; ++k) dst[n][k] = *(const LAS bf16x8*)(lds + PG8_SB(b, h) + boff + n * 2048 + k * 1024); } while (0)
; #define PG8_MMA(ai, bj, At, Bt) do { __builtin_amdgcn_s_setprio(1); _Pragma("unroll") for (int m = 0; m < 4; ++m) _Pragma("unroll") for (int n = 0; n < 2; ++n) _Pragma("unroll") for (int k = 0; k < 2; ++k) \
;         acc[ai][bj][m][n] = __builtin_amdgcn_mfma_f32_16x16x32_bf16(Bt[n][k], At[m][k], acc[ai][bj][m][n], 0, 0, 0); __builtin_amdgcn_s_setprio(0); } while (0)
; #define PG8_WAIT_V(n) asm volatile("s_waitcnt vmcnt(" #n ")" ::: "memory")
; #define PG8_WAIT_L(n) asm volatile("s_waitcnt lgkmcnt(" #n ")" ::: "memory")
; #define PG8_BAR __builtin_amdgcn_s_barrier()
; #define PG8_SCHED __builtin_amdgcn_sched_barrier(0)
; template <class Epi, bool ALIGN_EPI>
; __device__ __forceinline__ void gemm_phase(LAS unsigned char* lds, const int tid, const Gemm g, const StaticOrder& S, const Epi& E) {
;     ...
;             PG8_WAIT_V(8); PG8_WAIT_L(0); PG8_BAR; PG8_MMA(1, 0, At, B0); PG8_MMA(1, 1, At, B1); PG8_BAR; PG8_SCHED;
;             PG8_LDB(B0, 1, 0); PG8_LDB(B1, 1, 1); PG8_SCHED; PG8_LDA(At, 1, 0); PG8_STAGE(PG8_SA(0, 1), a2 + hstepA, voffA);
;             PG8_WAIT_V(8); PG8_WAIT_L(0); PG8_BAR; PG8_MMA(0, 0, At, B0); PG8_MMA(0, 1, At, B1); PG8_BAR; PG8_SCHED;
	s_setprio 1
	s_waitcnt lgkmcnt(0)
	v_mfma_f32_16x16x32_bf16 v[64:67], v[132:135], v[164:167], v[64:67]
	v_mfma_f32_16x16x32_bf16 v[60:63], v[140:143], v[164:167], v[60:63]
	v_mfma_f32_16x16x32_bf16 v[48:51], v[132:135], v[172:175], v[48:51]
	v_mfma_f32_16x16x32_bf16 v[44:47], v[140:143], v[172:175], v[44:47]
	v_mfma_f32_16x16x32_bf16 v[32:35], v[132:135], v[180:183], v[32:35]
	v_mfma_f32_16x16x32_bf16 v[28:31], v[140:143], v[180:183], v[28:31]
	v_mfma_f32_16x16x32_bf16 v[16:19], v[132:135], v[188:191], v[16:19]
	v_mfma_f32_16x16x32_bf16 v[12:15], v[140:143], v[188:191], v[12:15]
	v_mfma_f32_16x16x32_bf16 v[64:67], v[136:139], v[168:171], v[64:67]
	v_mfma_f32_16x16x32_bf16 v[60:63], v[144:147], v[168:171], v[60:63]
	v_mfma_f32_16x16x32_bf16 v[48:51], v[136:139], v[176:179], v[48:51]
	v_mfma_f32_16x16x32_bf16 v[44:47], v[144:147], v[176:179], v[44:47]
	v_mfma_f32_16x16x32_bf16 v[32:35], v[136:139], v[184:187], v[32:35]
	v_mfma_f32_16x16x32_bf16 v[28:31], v[144:147], v[184:187], v[28:31]
	v_mfma_f32_16x16x32_bf16 v[16:19], v[136:139], v[192:195], v[16:19]
	v_mfma_f32_16x16x32_bf16 v[12:15], v[144:147], v[192:195], v[12:15]
	s_setprio 0
	s_setprio 1
	v_mfma_f32_16x16x32_bf16 v[56:59], v[148:151], v[164:167], v[56:59]
	v_mfma_f32_16x16x32_bf16 v[52:55], v[156:159], v[164:167], v[52:55]
	v_mfma_f32_16x16x32_bf16 v[40:43], v[148:151], v[172:175], v[40:43]
	v_mfma_f32_16x16x32_bf16 v[36:39], v[156:159], v[172:175], v[36:39]
	v_mfma_f32_16x16x32_bf16 v[24:27], v[148:151], v[180:183], v[24:27]
	v_mfma_f32_16x16x32_bf16 v[20:23], v[156:159], v[180:183], v[20:23]
	v_mfma_f32_16x16x32_bf16 v[8:11], v[148:151], v[188:191], v[8:11]
	v_mfma_f32_16x16x32_bf16 v[2:5], v[156:159], v[188:191], v[4:7]
	v_mfma_f32_16x16x32_bf16 v[56:59], v[152:155], v[168:171], v[56:59]
	v_mfma_f32_16x16x32_bf16 v[52:55], v[160:163], v[168:171], v[52:55]
	v_mfma_f32_16x16x32_bf16 v[40:43], v[152:155], v[176:179], v[40:43]
	v_mfma_f32_16x16x32_bf16 v[36:39], v[160:163], v[176:179], v[36:39]
	v_mfma_f32_16x16x32_bf16 v[24:27], v[152:155], v[184:187], v[24:27]
	v_mfma_f32_16x16x32_bf16 v[20:23], v[160:163], v[184:187], v[20:23]
	v_mfma_f32_16x16x32_bf16 v[8:11], v[152:155], v[192:195], v[8:11]
	v_mfma_f32_16x16x32_bf16 v[2:5], v[160:163], v[192:195], v[2:5]
	s_setprio 0
	s_barrier
	s_add_i32 s94, 0, 0x18000
	v_add_u32_e32 v0, s94, v205
	s_add_i32 s95, 0, 0x1c000
	ds_read_b128 v[132:135], v0
	ds_read_b128 v[136:139], v0 offset:1024
	ds_read_b128 v[140:143], v0 offset:2048
	ds_read_b128 v[144:147], v0 offset:3072
	v_add_u32_e32 v0, s95, v205
	ds_read_b128 v[148:151], v0
	ds_read_b128 v[152:155], v0 offset:1024
	ds_read_b128 v[156:159], v0 offset:2048
	ds_read_b128 v[160:163], v0 offset:3072
	s_mov_b32 m0, s68
	s_nop 0
	global_load_lds_dwordx4 v[244:245], off
	s_mov_b32 m0, s69
	s_nop 0
	global_load_lds_dwordx4 v[246:247], off
	s_add_u32 s54, s54, 0x80000
	s_addc_u32 s55, s55, 0
	s_mov_b32 m0, s70
	v_lshl_add_u64 v[6:7], s[54:55], 0, v[210:211]
	ds_read_b128 v[164:167], v209 offset:32768
	ds_read_b128 v[168:171], v209 offset:33792
	ds_read_b128 v[172:175], v209 offset:34816
	ds_read_b128 v[176:179], v209 offset:35840
	ds_read_b128 v[180:183], v209 offset:36864
	ds_read_b128 v[184:187], v209 offset:37888
	ds_read_b128 v[188:191], v209 offset:38912
	ds_read_b128 v[192:195], v209 offset:39936
	global_load_lds_dwordx4 v[6:7], off
	v_lshl_add_u64 v[6:7], s[54:55], 0, v[214:215]
	s_mov_b32 m0, s71
	s_nop 0
	global_load_lds_dwordx4 v[6:7], off
	s_waitcnt vmcnt(8)
	s_waitcnt lgkmcnt(0)
	s_barrier
; #define PG8_STAGE(bufoff, gbase, voff) do { _Pragma("unroll") for (int _i = 0; _i < 2; ++_i) \
;         __builtin_amdgcn_global_load_lds((const unsigned*)((const char*)(gbase) + (voff)[_i]), (LAS unsigned*)(lds + (bufoff) + ldsw + _i * 8192), 16, 0, 0); } while (0)
; #define PG8_LDA(dst, b, h) do { _Pragma("unroll") for (int m = 0; m < 4; ++m) _Pragma("unroll") for (int k = 0; k < 2; ++k) dst[m][k] = *(const LAS bf16x8*)(lds + PG8_SA(b, h) + aoff + m * 2048 + k * 1024); } while (0)
; #define PG8_MMA(ai, bj, At, Bt) do { __builtin_amdgcn_s_setprio(1); _Pragma("unroll") for (int m = 0; m < 4; ++m) _Pragma("unroll") for (int n = 0; n < 2; ++n) _Pragma("unroll") for (int k = 0; k < 2; ++k) \
;         acc[ai][bj][m][n] = __builtin_amdgcn_mfma_f32_16x16x32_bf16(Bt[n][k], At[m][k], acc[ai][bj][m][n], 0, 0, 0); __builtin_amdgcn_s_setprio(0); } while (0)
; #define PG8_WAIT_V(n) asm volatile("s_waitcnt vmcnt(" #n ")" ::: "memory")
; #define PG8_WAIT_L(n) asm volatile("s_waitcnt lgkmcnt(" #n ")" ::: "memory")
; #define PG8_BAR __builtin_amdgcn_s_barrier()
; #define PG8_SCHED __builtin_amdgcn_sched_barrier(0)
; template <class Epi, bool ALIGN_EPI>
; __device__ __forceinline__ void gemm_phase(LAS unsigned char* lds, const int tid, const Gemm g, const StaticOrder& S, const Epi& E) {
;     ...
;             PG8_WAIT_V(8); PG8_WAIT_L(0); PG8_BAR; PG8_MMA(0, 0, At, B0); PG8_MMA(0, 1, At, B1); PG8_BAR; PG8_SCHED;
;             PG8_LDA(At, 1, 1); PG8_STAGE(PG8_SB(1, 0), b3, voffB); PG8_STAGE(PG8_SB(1, 1), b3 + hstepB, voffB); PG8_STAGE(PG8_SA(1, 0), a3, voffA);
;             PG8_WAIT_V(8); PG8_WAIT_L(0); PG8_BAR; PG8_MMA(1, 0, At, B0); PG8_MMA(1, 1, At, B1); PG8_BAR; PG8_SCHED;
;         }
;         if constexpr (ALIGN_EPI) { if (wr == 0) PG8_BAR; }
	s_setprio 1
	s_waitcnt lgkmcnt(0)
	v_mfma_f32_16x16x32_bf16 v[128:131], v[132:135], v[164:167], v[128:131]
	v_mfma_f32_16x16x32_bf16 v[124:127], v[140:143], v[164:167], v[124:127]
	v_mfma_f32_16x16x32_bf16 v[112:115], v[132:135], v[172:175], v[112:115]
	v_mfma_f32_16x16x32_bf16 v[108:111], v[140:143], v[172:175], v[108:111]
	v_mfma_f32_16x16x32_bf16 v[96:99], v[132:135], v[180:183], v[96:99]
	v_mfma_f32_16x16x32_bf16 v[92:95], v[140:143], v[180:183], v[92:95]
	v_mfma_f32_16x16x32_bf16 v[80:83], v[132:135], v[188:191], v[80:83]
	v_mfma_f32_16x16x32_bf16 v[76:79], v[140:143], v[188:191], v[76:79]
	v_mfma_f32_16x16x32_bf16 v[128:131], v[136:139], v[168:171], v[128:131]
	v_mfma_f32_16x16x32_bf16 v[124:127], v[144:147], v[168:171], v[124:127]
	v_mfma_f32_16x16x32_bf16 v[112:115], v[136:139], v[176:179], v[112:115]
	v_mfma_f32_16x16x32_bf16 v[108:111], v[144:147], v[176:179], v[108:111]
	v_mfma_f32_16x16x32_bf16 v[96:99], v[136:139], v[184:187], v[96:99]
	v_mfma_f32_16x16x32_bf16 v[92:95], v[144:147], v[184:187], v[92:95]
	v_mfma_f32_16x16x32_bf16 v[80:83], v[136:139], v[192:195], v[80:83]
	v_mfma_f32_16x16x32_bf16 v[76:79], v[144:147], v[192:195], v[76:79]
	s_setprio 0
	s_setprio 1
	v_mfma_f32_16x16x32_bf16 v[120:123], v[148:151], v[164:167], v[120:123]
	v_mfma_f32_16x16x32_bf16 v[116:119], v[156:159], v[164:167], v[116:119]
	v_mfma_f32_16x16x32_bf16 v[104:107], v[148:151], v[172:175], v[104:107]
	v_mfma_f32_16x16x32_bf16 v[100:103], v[156:159], v[172:175], v[100:103]
	v_mfma_f32_16x16x32_bf16 v[88:91], v[148:151], v[180:183], v[88:91]
	v_mfma_f32_16x16x32_bf16 v[84:87], v[156:159], v[180:183], v[84:87]
	v_mfma_f32_16x16x32_bf16 v[72:75], v[148:151], v[188:191], v[72:75]
	v_mfma_f32_16x16x32_bf16 v[68:71], v[156:159], v[188:191], v[68:71]
	v_mfma_f32_16x16x32_bf16 v[120:123], v[152:155], v[168:171], v[120:123]
	v_mfma_f32_16x16x32_bf16 v[116:119], v[160:163], v[168:171], v[116:119]
	v_mfma_f32_16x16x32_bf16 v[104:107], v[152:155], v[176:179], v[104:107]
	v_mfma_f32_16x16x32_bf16 v[100:103], v[160:163], v[176:179], v[100:103]
	v_mfma_f32_16x16x32_bf16 v[88:91], v[152:155], v[184:187], v[88:91]
	v_mfma_f32_16x16x32_bf16 v[84:87], v[160:163], v[184:187], v[84:87]
	v_mfma_f32_16x16x32_bf16 v[72:75], v[152:155], v[192:195], v[72:75]
	v_mfma_f32_16x16x32_bf16 v[68:71], v[160:163], v[192:195], v[68:71]
	s_setprio 0
	s_barrier
	s_add_i32 s54, s94, s67
	v_lshl_add_u64 v[6:7], v[240:241], 0, s[42:43]
	s_mov_b32 m0, s54
	ds_read_b128 v[164:167], v209 offset:49152
	ds_read_b128 v[168:171], v209 offset:50176
	ds_read_b128 v[172:175], v209 offset:51200
	ds_read_b128 v[176:179], v209 offset:52224
	ds_read_b128 v[180:183], v209 offset:53248
	ds_read_b128 v[184:187], v209 offset:54272
	ds_read_b128 v[188:191], v209 offset:55296
	ds_read_b128 v[192:195], v209 offset:56320
	global_load_lds_dwordx4 v[6:7], off
	s_add_i32 m0, s54, 0x2000
	s_add_u32 s34, s34, 0x80080
	v_lshl_add_u64 v[6:7], v[242:243], 0, s[42:43]
	s_addc_u32 s35, s35, 0
	s_add_i32 s54, s95, s67
	global_load_lds_dwordx4 v[6:7], off
	v_lshl_add_u64 v[6:7], s[34:35], 0, v[212:213]
	s_mov_b32 m0, s54
	s_nop 0
	global_load_lds_dwordx4 v[6:7], off
	v_lshl_add_u64 v[6:7], s[34:35], 0, v[216:217]
	s_add_i32 m0, s54, 0x2000
	s_nop 0
	global_load_lds_dwordx4 v[6:7], off
	s_waitcnt vmcnt(4)
	s_waitcnt lgkmcnt(0)
	s_barrier
	s_setprio 1
	s_waitcnt lgkmcnt(0)
	v_mfma_f32_16x16x32_bf16 v[64:67], v[132:135], v[164:167], v[64:67]
	v_mfma_f32_16x16x32_bf16 v[60:63], v[140:143], v[164:167], v[60:63]
	v_mfma_f32_16x16x32_bf16 v[48:51], v[132:135], v[172:175], v[48:51]
	v_mfma_f32_16x16x32_bf16 v[44:47], v[140:143], v[172:175], v[44:47]
	v_mfma_f32_16x16x32_bf16 v[32:35], v[132:135], v[180:183], v[32:35]
	v_mfma_f32_16x16x32_bf16 v[28:31], v[140:143], v[180:183], v[28:31]
	v_mfma_f32_16x16x32_bf16 v[16:19], v[132:135], v[188:191], v[16:19]
	v_mfma_f32_16x16x32_bf16 v[12:15], v[140:143], v[188:191], v[12:15]
	v_mfma_f32_16x16x32_bf16 v[64:67], v[136:139], v[168:171], v[64:67]
	v_mfma_f32_16x16x32_bf16 v[60:63], v[144:147], v[168:171], v[60:63]
	v_mfma_f32_16x16x32_bf16 v[48:51], v[136:139], v[176:179], v[48:51]
	v_mfma_f32_16x16x32_bf16 v[44:47], v[144:147], v[176:179], v[44:47]
	v_mfma_f32_16x16x32_bf16 v[32:35], v[136:139], v[184:187], v[32:35]
	v_mfma_f32_16x16x32_bf16 v[28:31], v[144:147], v[184:187], v[28:31]
	v_mfma_f32_16x16x32_bf16 v[16:19], v[136:139], v[192:195], v[16:19]
	v_mfma_f32_16x16x32_bf16 v[12:15], v[144:147], v[192:195], v[12:15]
	s_setprio 0
	s_setprio 1
	v_mfma_f32_16x16x32_bf16 v[56:59], v[148:151], v[164:167], v[56:59]
	v_mfma_f32_16x16x32_bf16 v[52:55], v[156:159], v[164:167], v[52:55]
	v_mfma_f32_16x16x32_bf16 v[40:43], v[148:151], v[172:175], v[40:43]
	v_mfma_f32_16x16x32_bf16 v[36:39], v[156:159], v[172:175], v[36:39]
	v_mfma_f32_16x16x32_bf16 v[24:27], v[148:151], v[180:183], v[24:27]
	v_mfma_f32_16x16x32_bf16 v[20:23], v[156:159], v[180:183], v[20:23]
	v_mfma_f32_16x16x32_bf16 v[6:9], v[148:151], v[188:191], v[8:11]
	v_mfma_f32_16x16x32_bf16 v[2:5], v[156:159], v[188:191], v[2:5]
	v_mfma_f32_16x16x32_bf16 v[56:59], v[152:155], v[168:171], v[56:59]
	v_mfma_f32_16x16x32_bf16 v[52:55], v[160:163], v[168:171], v[52:55]
	v_mfma_f32_16x16x32_bf16 v[40:43], v[152:155], v[176:179], v[40:43]
	v_mfma_f32_16x16x32_bf16 v[36:39], v[160:163], v[176:179], v[36:39]
	v_mfma_f32_16x16x32_bf16 v[24:27], v[152:155], v[184:187], v[24:27]
	v_mfma_f32_16x16x32_bf16 v[20:23], v[160:163], v[184:187], v[20:23]
	v_mfma_f32_16x16x32_bf16 v[8:11], v[152:155], v[192:195], v[6:9]
	v_mfma_f32_16x16x32_bf16 v[4:7], v[160:163], v[192:195], v[2:5]
	s_setprio 0
	s_barrier
	s_add_u32 s92, s92, 0x400
	s_addc_u32 s93, s93, 0
	s_add_u32 s21, s21, 0x100
	s_addc_u32 s36, s36, 0
	s_add_u32 s30, s30, 0x100
	s_addc_u32 s31, s31, 0
	s_cmp_ge_u32 s5, s19
	s_cbranch_scc1 .LBB0_266

; #define PG8_STAGE(bufoff, gbase, voff) do { _Pragma("unroll") for (int _i = 0; _i < 2; ++_i) \
;         __builtin_amdgcn_global_load_lds((const unsigned*)((const char*)(gbase) + (voff)[_i]), (LAS unsigned*)(lds + (bufoff) + ldsw + _i * 8192), 16, 0, 0); } while (0)
; #define PG8_LDA(dst, b, h) do { _Pragma("unroll") for (int m = 0; m < 4; ++m) _Pragma("unroll") for (int k = 0; k < 2; ++k) dst[m][k] = *(const LAS bf16x8*)(lds + PG8_SA(b, h) + aoff + m * 2048 + k * 1024); } while (0)
; #define PG8_LDB(dst, b, h) do { _Pragma("unroll") for (int n = 0; n < 2; ++n) _Pragma("unroll") for (int k = 0; k < 2; ++k) dst[n][k] = *(const LAS bf16x8*)(lds + PG8_SB(b, h) + boff + n * 2048 + k * 1024); } while (0)
; #define PG8_MMA(ai, bj, At, Bt) do { __builtin_amdgcn_s_setprio(1); _Pragma("unroll") for (int m = 0; m < 4; ++m) _Pragma("unroll") for (int n = 0; n < 2; ++n) _Pragma("unroll") for (int k = 0; k < 2; ++k) \
;         acc[ai][bj][m][n] = __builtin_amdgcn_mfma_f32_16x16x32_bf16(Bt[n][k], At[m][k], acc[ai][bj][m][n], 0, 0, 0); __builtin_amdgcn_s_setprio(0); } while (0)
; #define PG8_WAIT_V(n) asm volatile("s_waitcnt vmcnt(" #n ")" ::: "memory")
; #define PG8_BAR __builtin_amdgcn_s_barrier()
; template <class Epi, bool ALIGN_EPI>
; __device__ __forceinline__ void gemm_phase(LAS unsigned char* lds, const int tid, const Gemm g, const StaticOrder& S, const Epi& E) {
;     ...
;         for (int t = 0; t < nt; t += 2) {
;             if constexpr (Epi::HOOK) { if (t != 0 && (t & 7) == 0) E.hook(acc, cur, (t >> 3) - 1, wr, wc, fr, fq); }
;             const bool last = (t == nt - 2);
;             const char* a1 = cA + (size_t)(t + 1) * kstepA;
;             const char* a2 = last ? nA : cA + (size_t)(t + 2) * kstepA; const char* b2 = last ? nB : cB + (size_t)(t + 2) * kstepB;
;             const char* a3 = a2 + kstepA; const char* b3 = b2 + kstepB;
;             PG8_LDB(B0, 0, 0); PG8_LDB(B1, 0, 1); PG8_SCHED; PG8_LDA(At, 0, 0); PG8_STAGE(PG8_SA(1, 1), a1 + hstepA, voffA);
;             PG8_WAIT_V(8); PG8_WAIT_L(0); PG8_BAR; PG8_MMA(0, 0, At, B0); PG8_MMA(0, 1, At, B1); PG8_BAR; PG8_SCHED;
;             PG8_LDA(At, 0, 1); PG8_STAGE(PG8_SB(0, 0), b2, voffB); PG8_STAGE(PG8_SB(0, 1), b2 + hstepB, voffB); PG8_STAGE(PG8_SA(0, 0), a2, voffA);
;             PG8_WAIT_V(8); PG8_WAIT_L(0); PG8_BAR; PG8_MMA(1, 0, At, B0); PG8_MMA(1, 1, At, B1); PG8_BAR; PG8_SCHED;
.LBB0_667:
	s_add_u32 s22, s20, 0xfff80080
	s_addc_u32 s23, s21, -1
	s_add_i32 s49, 0, 0x10000
	s_cmp_eq_u32 s19, 28
	s_cselect_b32 s25, s15, s23
	s_cselect_b32 s24, s14, s22
	v_add_u32_e32 v0, s49, v173
	s_cselect_b32 s23, s17, s13
	s_cselect_b32 s22, s16, s11
	s_add_i32 s52, 0, 0x14000
	ds_read_b128 v[130:133], v0
	ds_read_b128 v[134:137], v0 offset:1024
	ds_read_b128 v[138:141], v0 offset:2048
	ds_read_b128 v[142:145], v0 offset:3072
	v_add_u32_e32 v0, s52, v173
	ds_read_b128 v[158:161], v0
	ds_read_b128 v[162:165], v0 offset:1024
	ds_read_b128 v[166:169], v0 offset:2048
	ds_read_b128 v[178:181], v0 offset:3072
	v_lshl_add_u64 v[170:171], s[20:21], 0, v[156:157]
	s_add_i32 m0, s28, 0xc000
	ds_read_b128 v[182:185], v176
	ds_read_b128 v[186:189], v176 offset:1024
	ds_read_b128 v[190:193], v176 offset:2048
	ds_read_b128 v[208:211], v176 offset:3072
	ds_read_b128 v[212:215], v176 offset:4096
	ds_read_b128 v[216:219], v176 offset:5120
	ds_read_b128 v[220:223], v176 offset:6144
	ds_read_b128 v[240:243], v176 offset:7168
	global_load_lds_dwordx4 v[170:171], off
	v_lshl_add_u64 v[170:171], s[20:21], 0, v[154:155]
	s_add_i32 m0, s28, 0xe000
	s_nop 0
	global_load_lds_dwordx4 v[170:171], off
	s_sub_u32 s98, s20, 0x80000
	s_subb_u32 s99, s21, 0
	v_lshl_add_u64 v[170:171], s[98:99], 0, v[156:157]
	s_mov_b32 m0, s34
	s_nop 0
	global_load_lds_dwordx4 v[170:171], off
	v_lshl_add_u64 v[170:171], s[98:99], 0, v[154:155]
	s_mov_b32 m0, s35
	s_nop 0
	global_load_lds_dwordx4 v[170:171], off
	s_waitcnt vmcnt(8)
	s_waitcnt lgkmcnt(0)
	s_barrier
	s_setprio 1
	s_waitcnt lgkmcnt(0)
	v_mfma_f32_16x16x32_bf16 v[126:129], v[130:133], v[182:185], v[126:129]
	v_mfma_f32_16x16x32_bf16 v[122:125], v[138:141], v[182:185], v[122:125]
	v_mfma_f32_16x16x32_bf16 v[118:121], v[130:133], v[190:193], v[118:121]
	v_mfma_f32_16x16x32_bf16 v[114:117], v[138:141], v[190:193], v[114:117]
	v_mfma_f32_16x16x32_bf16 v[102:105], v[130:133], v[212:215], v[102:105]
	v_mfma_f32_16x16x32_bf16 v[98:101], v[138:141], v[212:215], v[98:101]
	v_mfma_f32_16x16x32_bf16 v[86:89], v[130:133], v[220:223], v[86:89]
	v_mfma_f32_16x16x32_bf16 v[82:85], v[138:141], v[220:223], v[82:85]
	v_mfma_f32_16x16x32_bf16 v[126:129], v[134:137], v[186:189], v[126:129]
	v_mfma_f32_16x16x32_bf16 v[122:125], v[142:145], v[186:189], v[122:125]
	v_mfma_f32_16x16x32_bf16 v[118:121], v[134:137], v[208:211], v[118:121]
	v_mfma_f32_16x16x32_bf16 v[114:117], v[142:145], v[208:211], v[114:117]
	v_mfma_f32_16x16x32_bf16 v[102:105], v[134:137], v[216:219], v[102:105]
	v_mfma_f32_16x16x32_bf16 v[98:101], v[142:145], v[216:219], v[98:101]
	v_mfma_f32_16x16x32_bf16 v[86:89], v[134:137], v[240:243], v[86:89]
	v_mfma_f32_16x16x32_bf16 v[82:85], v[142:145], v[240:243], v[82:85]
	s_setprio 0
	s_setprio 1
	v_mfma_f32_16x16x32_bf16 v[110:113], v[158:161], v[182:185], v[110:113]
	v_mfma_f32_16x16x32_bf16 v[106:109], v[166:169], v[182:185], v[106:109]
	v_mfma_f32_16x16x32_bf16 v[94:97], v[158:161], v[190:193], v[94:97]
	v_mfma_f32_16x16x32_bf16 v[90:93], v[166:169], v[190:193], v[90:93]
	v_mfma_f32_16x16x32_bf16 v[78:81], v[158:161], v[212:215], v[78:81]
	v_mfma_f32_16x16x32_bf16 v[74:77], v[166:169], v[212:215], v[74:77]
	v_mfma_f32_16x16x32_bf16 v[70:73], v[158:161], v[220:223], v[70:73]
	v_mfma_f32_16x16x32_bf16 v[66:69], v[166:169], v[220:223], v[66:69]
	v_mfma_f32_16x16x32_bf16 v[110:113], v[162:165], v[186:189], v[110:113]
	v_mfma_f32_16x16x32_bf16 v[106:109], v[178:181], v[186:189], v[106:109]
	v_mfma_f32_16x16x32_bf16 v[94:97], v[162:165], v[208:211], v[94:97]
	v_mfma_f32_16x16x32_bf16 v[90:93], v[178:181], v[208:211], v[90:93]
	v_mfma_f32_16x16x32_bf16 v[78:81], v[162:165], v[216:219], v[78:81]
	v_mfma_f32_16x16x32_bf16 v[74:77], v[178:181], v[216:219], v[74:77]
	v_mfma_f32_16x16x32_bf16 v[70:73], v[162:165], v[240:243], v[70:73]
	v_mfma_f32_16x16x32_bf16 v[66:69], v[178:181], v[240:243], v[66:69]
	s_setprio 0
	s_barrier
	s_add_i32 s49, s49, s27
	v_lshl_add_u64 v[170:171], s[22:23], 0, v[148:149]
	s_mov_b32 m0, s49
	ds_read_b128 v[182:185], v176 offset:16384
	ds_read_b128 v[186:189], v176 offset:17408
	ds_read_b128 v[190:193], v176 offset:18432
	ds_read_b128 v[208:211], v176 offset:19456
	ds_read_b128 v[212:215], v176 offset:20480
	ds_read_b128 v[216:219], v176 offset:21504
	ds_read_b128 v[220:223], v176 offset:22528
	ds_read_b128 v[240:243], v176 offset:23552
	global_load_lds_dwordx4 v[170:171], off
	s_add_i32 m0, s49, 0x2000
	s_add_u32 s54, s22, 0x80000
	v_lshl_add_u64 v[194:195], s[22:23], 0, v[152:153]
	s_addc_u32 s55, s23, 0
	s_add_i32 s49, s52, s27
	global_load_lds_dwordx4 v[194:195], off
	v_lshl_add_u64 v[224:225], s[54:55], 0, v[148:149]
	s_mov_b32 m0, s49
	v_lshl_add_u64 v[244:245], s[24:25], 0, v[150:151]
	global_load_lds_dwordx4 v[224:225], off
	v_lshl_add_u64 v[224:225], s[54:55], 0, v[152:153]
	s_add_i32 m0, s49, 0x2000
	s_nop 0
	global_load_lds_dwordx4 v[224:225], off
	v_lshl_add_u64 v[224:225], s[24:25], 0, v[146:147]
	s_waitcnt vmcnt(4)
	s_waitcnt lgkmcnt(0)
	s_barrier
; #define PG8_STAGE(bufoff, gbase, voff) do { _Pragma("unroll") for (int _i = 0; _i < 2; ++_i) \
;         __builtin_amdgcn_global_load_lds((const unsigned*)((const char*)(gbase) + (voff)[_i]), (LAS unsigned*)(lds + (bufoff) + ldsw + _i * 8192), 16, 0, 0); } while (0)
; #define PG8_LDA(dst, b, h) do { _Pragma("unroll") for (int m = 0; m < 4; ++m) _Pragma("unroll") for (int k = 0; k < 2; ++k) dst[m][k] = *(const LAS bf16x8*)(lds + PG8_SA(b, h) + aoff + m * 2048 + k * 1024); } while (0)
; #define PG8_LDB(dst, b, h) do { _Pragma("unroll") for (int n = 0; n < 2; ++n) _Pragma("unroll") for (int k = 0; k < 2; ++k) dst[n][k] = *(const LAS bf16x8*)(lds + PG8_SB(b, h) + boff + n * 2048 + k * 1024); } while (0)
; #define PG8_MMA(ai, bj, At, Bt) do { __builtin_amdgcn_s_setprio(1); _Pragma("unroll") for (int m = 0; m < 4; ++m) _Pragma("unroll") for (int n = 0; n < 2; ++n) _Pragma("unroll") for (int k = 0; k < 2; ++k) \
;         acc[ai][bj][m][n] = __builtin_amdgcn_mfma_f32_16x16x32_bf16(Bt[n][k], At[m][k], acc[ai][bj][m][n], 0, 0, 0); __builtin_amdgcn_s_setprio(0); } while (0)
; #define PG8_WAIT_V(n) asm volatile("s_waitcnt vmcnt(" #n ")" ::: "memory")
; #define PG8_WAIT_L(n) asm volatile("s_waitcnt lgkmcnt(" #n ")" ::: "memory")
; #define PG8_BAR __builtin_amdgcn_s_barrier()
; #define PG8_SCHED __builtin_amdgcn_sched_barrier(0)
; template <class Epi, bool ALIGN_EPI>
; __device__ __forceinline__ void gemm_phase(LAS unsigned char* lds, const int tid, const Gemm g, const StaticOrder& S, const Epi& E) {
;     ...
;             PG8_WAIT_V(8); PG8_WAIT_L(0); PG8_BAR; PG8_MMA(1, 0, At, B0); PG8_MMA(1, 1, At, B1); PG8_BAR; PG8_SCHED;
;             PG8_LDB(B0, 1, 0); PG8_LDB(B1, 1, 1); PG8_SCHED; PG8_LDA(At, 1, 0); PG8_STAGE(PG8_SA(0, 1), a2 + hstepA, voffA);
;             PG8_WAIT_V(8); PG8_WAIT_L(0); PG8_BAR; PG8_MMA(0, 0, At, B0); PG8_MMA(0, 1, At, B1); PG8_BAR; PG8_SCHED;
	s_setprio 1
	s_waitcnt lgkmcnt(0)
	v_mfma_f32_16x16x32_bf16 v[62:65], v[130:133], v[182:185], v[62:65]
	v_mfma_f32_16x16x32_bf16 v[58:61], v[138:141], v[182:185], v[58:61]
	v_mfma_f32_16x16x32_bf16 v[54:57], v[130:133], v[190:193], v[54:57]
	v_mfma_f32_16x16x32_bf16 v[50:53], v[138:141], v[190:193], v[50:53]
	v_mfma_f32_16x16x32_bf16 v[38:41], v[130:133], v[212:215], v[38:41]
	v_mfma_f32_16x16x32_bf16 v[34:37], v[138:141], v[212:215], v[34:37]
	v_mfma_f32_16x16x32_bf16 v[22:25], v[130:133], v[220:223], v[22:25]
	v_mfma_f32_16x16x32_bf16 v[18:21], v[138:141], v[220:223], v[18:21]
	v_mfma_f32_16x16x32_bf16 v[62:65], v[134:137], v[186:189], v[62:65]
	v_mfma_f32_16x16x32_bf16 v[58:61], v[142:145], v[186:189], v[58:61]
	v_mfma_f32_16x16x32_bf16 v[54:57], v[134:137], v[208:211], v[54:57]
	v_mfma_f32_16x16x32_bf16 v[50:53], v[142:145], v[208:211], v[50:53]
	v_mfma_f32_16x16x32_bf16 v[38:41], v[134:137], v[216:219], v[38:41]
	v_mfma_f32_16x16x32_bf16 v[34:37], v[142:145], v[216:219], v[34:37]
	v_mfma_f32_16x16x32_bf16 v[22:25], v[134:137], v[240:243], v[22:25]
	v_mfma_f32_16x16x32_bf16 v[18:21], v[142:145], v[240:243], v[18:21]
	s_setprio 0
	s_setprio 1
	v_mfma_f32_16x16x32_bf16 v[46:49], v[158:161], v[182:185], v[46:49]
	v_mfma_f32_16x16x32_bf16 v[42:45], v[166:169], v[182:185], v[42:45]
	v_mfma_f32_16x16x32_bf16 v[30:33], v[158:161], v[190:193], v[30:33]
	v_mfma_f32_16x16x32_bf16 v[26:29], v[166:169], v[190:193], v[26:29]
	v_mfma_f32_16x16x32_bf16 v[14:17], v[158:161], v[212:215], v[14:17]
	v_mfma_f32_16x16x32_bf16 v[10:13], v[166:169], v[212:215], v[10:13]
	v_mfma_f32_16x16x32_bf16 v[6:9], v[158:161], v[220:223], v[6:9]
	v_mfma_f32_16x16x32_bf16 v[2:5], v[166:169], v[220:223], v[2:5]
	v_mfma_f32_16x16x32_bf16 v[46:49], v[162:165], v[186:189], v[46:49]
	v_mfma_f32_16x16x32_bf16 v[42:45], v[178:181], v[186:189], v[42:45]
	v_mfma_f32_16x16x32_bf16 v[30:33], v[162:165], v[208:211], v[30:33]
	v_mfma_f32_16x16x32_bf16 v[26:29], v[178:181], v[208:211], v[26:29]
	v_mfma_f32_16x16x32_bf16 v[14:17], v[162:165], v[216:219], v[14:17]
	v_mfma_f32_16x16x32_bf16 v[10:13], v[178:181], v[216:219], v[10:13]
	v_mfma_f32_16x16x32_bf16 v[6:9], v[162:165], v[240:243], v[6:9]
	v_mfma_f32_16x16x32_bf16 v[2:5], v[178:181], v[240:243], v[2:5]
	s_setprio 0
	s_barrier
	s_add_i32 s49, 0, 0x18000
	v_add_u32_e32 v0, s49, v173
	s_add_i32 s52, 0, 0x1c000
	ds_read_b128 v[130:133], v0
	ds_read_b128 v[134:137], v0 offset:1024
	ds_read_b128 v[138:141], v0 offset:2048
	ds_read_b128 v[142:145], v0 offset:3072
	v_add_u32_e32 v0, s52, v173
	ds_read_b128 v[158:161], v0
	ds_read_b128 v[162:165], v0 offset:1024
	ds_read_b128 v[166:169], v0 offset:2048
	ds_read_b128 v[178:181], v0 offset:3072
	s_mov_b32 m0, s28
	s_nop 0
	global_load_lds_dwordx4 v[224:225], off
	s_mov_b32 m0, s29
	s_nop 0
	global_load_lds_dwordx4 v[244:245], off
	s_add_u32 s24, s24, 0x80000
	s_addc_u32 s25, s25, 0
	s_mov_b32 m0, s30
	v_lshl_add_u64 v[246:247], s[24:25], 0, v[146:147]
	ds_read_b128 v[182:185], v176 offset:32768
	ds_read_b128 v[186:189], v176 offset:33792
	ds_read_b128 v[190:193], v176 offset:34816
	ds_read_b128 v[208:211], v176 offset:35840
	ds_read_b128 v[212:215], v176 offset:36864
	ds_read_b128 v[216:219], v176 offset:37888
	ds_read_b128 v[220:223], v176 offset:38912
	ds_read_b128 v[240:243], v176 offset:39936
	global_load_lds_dwordx4 v[246:247], off
	v_lshl_add_u64 v[246:247], s[24:25], 0, v[150:151]
	s_mov_b32 m0, s31
	s_nop 0
	global_load_lds_dwordx4 v[246:247], off
	s_waitcnt vmcnt(8)
	s_waitcnt lgkmcnt(0)
	s_barrier
; #define PG8_STAGE(bufoff, gbase, voff) do { _Pragma("unroll") for (int _i = 0; _i < 2; ++_i) \
;         __builtin_amdgcn_global_load_lds((const unsigned*)((const char*)(gbase) + (voff)[_i]), (LAS unsigned*)(lds + (bufoff) + ldsw + _i * 8192), 16, 0, 0); } while (0)
; #define PG8_LDA(dst, b, h) do { _Pragma("unroll") for (int m = 0; m < 4; ++m) _Pragma("unroll") for (int k = 0; k < 2; ++k) dst[m][k] = *(const LAS bf16x8*)(lds + PG8_SA(b, h) + aoff + m * 2048 + k * 1024); } while (0)
; #define PG8_MMA(ai, bj, At, Bt) do { __builtin_amdgcn_s_setprio(1); _Pragma("unroll") for (int m = 0; m < 4; ++m) _Pragma("unroll") for (int n = 0; n < 2; ++n) _Pragma("unroll") for (int k = 0; k < 2; ++k) \
;         acc[ai][bj][m][n] = __builtin_amdgcn_mfma_f32_16x16x32_bf16(Bt[n][k], At[m][k], acc[ai][bj][m][n], 0, 0, 0); __builtin_amdgcn_s_setprio(0); } while (0)
; #define PG8_WAIT_V(n) asm volatile("s_waitcnt vmcnt(" #n ")" ::: "memory")
; #define PG8_WAIT_L(n) asm volatile("s_waitcnt lgkmcnt(" #n ")" ::: "memory")
; #define PG8_BAR __builtin_amdgcn_s_barrier()
; #define PG8_SCHED __builtin_amdgcn_sched_barrier(0)
; template <class Epi, bool ALIGN_EPI>
; __device__ __forceinline__ void gemm_phase(LAS unsigned char* lds, const int tid, const Gemm g, const StaticOrder& S, const Epi& E) {
;     ...
;             PG8_WAIT_V(8); PG8_WAIT_L(0); PG8_BAR; PG8_MMA(0, 0, At, B0); PG8_MMA(0, 1, At, B1); PG8_BAR; PG8_SCHED;
;             PG8_LDA(At, 1, 1); PG8_STAGE(PG8_SB(1, 0), b3, voffB); PG8_STAGE(PG8_SB(1, 1), b3 + hstepB, voffB); PG8_STAGE(PG8_SA(1, 0), a3, voffA);
;             PG8_WAIT_V(8); PG8_WAIT_L(0); PG8_BAR; PG8_MMA(1, 0, At, B0); PG8_MMA(1, 1, At, B1); PG8_BAR; PG8_SCHED;
;         }
;         if constexpr (ALIGN_EPI) { if (wr == 0) PG8_BAR; }
	s_setprio 1
	s_waitcnt lgkmcnt(0)
	v_mfma_f32_16x16x32_bf16 v[126:129], v[130:133], v[182:185], v[126:129]
	v_mfma_f32_16x16x32_bf16 v[122:125], v[138:141], v[182:185], v[122:125]
	v_mfma_f32_16x16x32_bf16 v[118:121], v[130:133], v[190:193], v[118:121]
	v_mfma_f32_16x16x32_bf16 v[114:117], v[138:141], v[190:193], v[114:117]
	v_mfma_f32_16x16x32_bf16 v[102:105], v[130:133], v[212:215], v[102:105]
	v_mfma_f32_16x16x32_bf16 v[98:101], v[138:141], v[212:215], v[98:101]
	v_mfma_f32_16x16x32_bf16 v[86:89], v[130:133], v[220:223], v[86:89]
	v_mfma_f32_16x16x32_bf16 v[82:85], v[138:141], v[220:223], v[82:85]
	v_mfma_f32_16x16x32_bf16 v[126:129], v[134:137], v[186:189], v[126:129]
	v_mfma_f32_16x16x32_bf16 v[122:125], v[142:145], v[186:189], v[122:125]
	v_mfma_f32_16x16x32_bf16 v[118:121], v[134:137], v[208:211], v[118:121]
	v_mfma_f32_16x16x32_bf16 v[114:117], v[142:145], v[208:211], v[114:117]
	v_mfma_f32_16x16x32_bf16 v[102:105], v[134:137], v[216:219], v[102:105]
	v_mfma_f32_16x16x32_bf16 v[98:101], v[142:145], v[216:219], v[98:101]
	v_mfma_f32_16x16x32_bf16 v[86:89], v[134:137], v[240:243], v[86:89]
	v_mfma_f32_16x16x32_bf16 v[82:85], v[142:145], v[240:243], v[82:85]
	s_setprio 0
	s_setprio 1
	v_mfma_f32_16x16x32_bf16 v[110:113], v[158:161], v[182:185], v[110:113]
	v_mfma_f32_16x16x32_bf16 v[106:109], v[166:169], v[182:185], v[106:109]
	v_mfma_f32_16x16x32_bf16 v[94:97], v[158:161], v[190:193], v[94:97]
	v_mfma_f32_16x16x32_bf16 v[90:93], v[166:169], v[190:193], v[90:93]
	v_mfma_f32_16x16x32_bf16 v[78:81], v[158:161], v[212:215], v[78:81]
	v_mfma_f32_16x16x32_bf16 v[74:77], v[166:169], v[212:215], v[74:77]
	v_mfma_f32_16x16x32_bf16 v[70:73], v[158:161], v[220:223], v[70:73]
	v_mfma_f32_16x16x32_bf16 v[66:69], v[166:169], v[220:223], v[66:69]
	v_mfma_f32_16x16x32_bf16 v[110:113], v[162:165], v[186:189], v[110:113]
	v_mfma_f32_16x16x32_bf16 v[106:109], v[178:181], v[186:189], v[106:109]
	v_mfma_f32_16x16x32_bf16 v[94:97], v[162:165], v[208:211], v[94:97]
	v_mfma_f32_16x16x32_bf16 v[90:93], v[178:181], v[208:211], v[90:93]
	v_mfma_f32_16x16x32_bf16 v[78:81], v[162:165], v[216:219], v[78:81]
	v_mfma_f32_16x16x32_bf16 v[74:77], v[178:181], v[216:219], v[74:77]
	v_mfma_f32_16x16x32_bf16 v[70:73], v[162:165], v[240:243], v[70:73]
	v_mfma_f32_16x16x32_bf16 v[66:69], v[178:181], v[240:243], v[66:69]
	s_setprio 0
	s_barrier
	s_add_i32 s24, s49, s27
	v_lshl_add_u64 v[170:171], v[170:171], 0, s[42:43]
	s_mov_b32 m0, s24
	ds_read_b128 v[182:185], v176 offset:49152
	ds_read_b128 v[186:189], v176 offset:50176
	ds_read_b128 v[190:193], v176 offset:51200
	ds_read_b128 v[208:211], v176 offset:52224
	ds_read_b128 v[212:215], v176 offset:53248
	ds_read_b128 v[216:219], v176 offset:54272
	ds_read_b128 v[220:223], v176 offset:55296
	ds_read_b128 v[240:243], v176 offset:56320
	global_load_lds_dwordx4 v[170:171], off
	s_add_i32 m0, s24, 0x2000
	s_add_u32 s22, s22, 0x80080
	v_lshl_add_u64 v[170:171], v[194:195], 0, s[42:43]
	s_addc_u32 s23, s23, 0
	s_add_i32 s24, s52, s27
	global_load_lds_dwordx4 v[170:171], off
	v_lshl_add_u64 v[170:171], s[22:23], 0, v[148:149]
	s_mov_b32 m0, s24
	s_nop 0
	global_load_lds_dwordx4 v[170:171], off
	v_lshl_add_u64 v[170:171], s[22:23], 0, v[152:153]
	s_add_i32 m0, s24, 0x2000
	s_nop 0
	global_load_lds_dwordx4 v[170:171], off
	s_waitcnt vmcnt(4)
	s_waitcnt lgkmcnt(0)
	s_barrier
	s_setprio 1
	s_waitcnt lgkmcnt(0)
	v_mfma_f32_16x16x32_bf16 v[62:65], v[130:133], v[182:185], v[62:65]
	v_mfma_f32_16x16x32_bf16 v[58:61], v[138:141], v[182:185], v[58:61]
	v_mfma_f32_16x16x32_bf16 v[54:57], v[130:133], v[190:193], v[54:57]
	v_mfma_f32_16x16x32_bf16 v[50:53], v[138:141], v[190:193], v[50:53]
	v_mfma_f32_16x16x32_bf16 v[38:41], v[130:133], v[212:215], v[38:41]
	v_mfma_f32_16x16x32_bf16 v[34:37], v[138:141], v[212:215], v[34:37]
	v_mfma_f32_16x16x32_bf16 v[22:25], v[130:133], v[220:223], v[22:25]
	v_mfma_f32_16x16x32_bf16 v[18:21], v[138:141], v[220:223], v[18:21]
	v_mfma_f32_16x16x32_bf16 v[62:65], v[134:137], v[186:189], v[62:65]
	v_mfma_f32_16x16x32_bf16 v[58:61], v[142:145], v[186:189], v[58:61]
	v_mfma_f32_16x16x32_bf16 v[54:57], v[134:137], v[208:211], v[54:57]
	v_mfma_f32_16x16x32_bf16 v[50:53], v[142:145], v[208:211], v[50:53]
	v_mfma_f32_16x16x32_bf16 v[38:41], v[134:137], v[216:219], v[38:41]
	v_mfma_f32_16x16x32_bf16 v[34:37], v[142:145], v[216:219], v[34:37]
	v_mfma_f32_16x16x32_bf16 v[22:25], v[134:137], v[240:243], v[22:25]
	v_mfma_f32_16x16x32_bf16 v[18:21], v[142:145], v[240:243], v[18:21]
	s_setprio 0
	s_setprio 1
	v_mfma_f32_16x16x32_bf16 v[46:49], v[158:161], v[182:185], v[46:49]
	v_mfma_f32_16x16x32_bf16 v[42:45], v[166:169], v[182:185], v[42:45]
	v_mfma_f32_16x16x32_bf16 v[30:33], v[158:161], v[190:193], v[30:33]
	v_mfma_f32_16x16x32_bf16 v[26:29], v[166:169], v[190:193], v[26:29]
	v_mfma_f32_16x16x32_bf16 v[14:17], v[158:161], v[212:215], v[14:17]
	v_mfma_f32_16x16x32_bf16 v[10:13], v[166:169], v[212:215], v[10:13]
	v_mfma_f32_16x16x32_bf16 v[6:9], v[158:161], v[220:223], v[6:9]
	v_mfma_f32_16x16x32_bf16 v[2:5], v[166:169], v[220:223], v[2:5]
	v_mfma_f32_16x16x32_bf16 v[46:49], v[162:165], v[186:189], v[46:49]
	v_mfma_f32_16x16x32_bf16 v[42:45], v[178:181], v[186:189], v[42:45]
	v_mfma_f32_16x16x32_bf16 v[30:33], v[162:165], v[208:211], v[30:33]
	v_mfma_f32_16x16x32_bf16 v[26:29], v[178:181], v[208:211], v[26:29]
	v_mfma_f32_16x16x32_bf16 v[14:17], v[162:165], v[216:219], v[14:17]
	v_mfma_f32_16x16x32_bf16 v[10:13], v[178:181], v[216:219], v[10:13]
	v_mfma_f32_16x16x32_bf16 v[6:9], v[162:165], v[240:243], v[6:9]
	v_mfma_f32_16x16x32_bf16 v[2:5], v[178:181], v[240:243], v[2:5]
	s_setprio 0
	s_barrier
	s_add_i32 s19, s19, 2
	s_add_u32 s11, s11, 0x100
	s_addc_u32 s13, s13, 0
	s_add_u32 s20, s20, 0x100
	s_addc_u32 s21, s21, 0
	s_cmp_gt_u32 s19, 29
	s_cbranch_scc0 .LBB0_667
	s_and_b64 vcc, exec, s[8:9]
	s_cbranch_vccz .LBB0_670
	s_barrier

; __global__ void __launch_bounds__(NTHREADS, 2) fwd_kernel(Args A) {
	.amdhsa_kernel _Z10fwd_kernel4Args
		.amdhsa_group_segment_fixed_size 0
		.amdhsa_private_segment_fixed_size 0
		.amdhsa_kernarg_size 448
		.amdhsa_user_sgpr_count 2
		.amdhsa_user_sgpr_dispatch_ptr 0
		.amdhsa_user_sgpr_queue_ptr 0
		.amdhsa_user_sgpr_kernarg_segment_ptr 1
		.amdhsa_user_sgpr_dispatch_id 0
		.amdhsa_user_sgpr_kernarg_preload_length 0
		.amdhsa_user_sgpr_kernarg_preload_offset 0
		.amdhsa_user_sgpr_private_segment_size 0
		.amdhsa_uses_dynamic_stack 0
		.amdhsa_enable_private_segment 0
		.amdhsa_system_sgpr_workgroup_id_x 1
		.amdhsa_system_sgpr_workgroup_id_y 0
		.amdhsa_system_sgpr_workgroup_id_z 0
		.amdhsa_system_sgpr_workgroup_info 0
		.amdhsa_system_vgpr_workitem_id 2
		.amdhsa_next_free_vgpr 250
		.amdhsa_next_free_sgpr 100
		.amdhsa_accum_offset 252
		.amdhsa_reserve_vcc 1
		.amdhsa_float_round_mode_32 0
		.amdhsa_float_round_mode_16_64 0
		.amdhsa_float_denorm_mode_32 3
		.amdhsa_float_denorm_mode_16_64 3
		.amdhsa_dx10_clamp 1
		.amdhsa_ieee_mode 1
		.amdhsa_fp16_overflow 0
		.amdhsa_tg_split 0
		.amdhsa_exception_fp_ieee_invalid_op 0
		.amdhsa_exception_fp_denorm_src 0
		.amdhsa_exception_fp_ieee_div_zero 0
		.amdhsa_exception_fp_ieee_overflow 0
		.amdhsa_exception_fp_ieee_underflow 0
		.amdhsa_exception_fp_ieee_inexact 0
		.amdhsa_exception_int_div_zero 0
	.end_amdhsa_kernel

; __global__ void __launch_bounds__(NTHREADS, 2) fwd_kernel(Args A) {
amdhsa.kernels:
  - .agpr_count:     0
    .args:
      - .offset:         0
        .size:           192
        .value_kind:     by_value
      - .offset:         192
        .size:           4
        .value_kind:     hidden_block_count_x
      - .offset:         196
        .size:           4
        .value_kind:     hidden_block_count_y
      - .offset:         200
        .size:           4
        .value_kind:     hidden_block_count_z
      - .offset:         204
        .size:           2
        .value_kind:     hidden_group_size_x
      - .offset:         206
        .size:           2
        .value_kind:     hidden_group_size_y
      - .offset:         208
        .size:           2
        .value_kind:     hidden_group_size_z
      - .offset:         210
        .size:           2
        .value_kind:     hidden_remainder_x
      - .offset:         212
        .size:           2
        .value_kind:     hidden_remainder_y
      - .offset:         214
        .size:           2
        .value_kind:     hidden_remainder_z
      - .offset:         232
        .size:           8
        .value_kind:     hidden_global_offset_x
      - .offset:         240
        .size:           8
        .value_kind:     hidden_global_offset_y
      - .offset:         248
        .size:           8
        .value_kind:     hidden_global_offset_z
      - .offset:         256
        .size:           2
        .value_kind:     hidden_grid_dims
      - .offset:         280
        .size:           8
        .value_kind:     hidden_multigrid_sync_arg
      - .offset:         312
        .size:           4
        .value_kind:     hidden_dynamic_lds_size
    .group_segment_fixed_size: 0
    .kernarg_segment_align: 8
    .kernarg_segment_size: 448
    .language:       OpenCL C
    .language_version:
      - 2
      - 0
    .max_flat_workgroup_size: 512
    .name:           _Z10fwd_kernel4Args
    .private_segment_fixed_size: 0
    .sgpr_count:     106
    .sgpr_spill_count: 75
    .symbol:         _Z10fwd_kernel4Args.kd
    .uniform_work_group_size: 1
    .uses_dynamic_stack: false
    .vgpr_count:     250
    .vgpr_spill_count: 0
    .wavefront_size: 64
